# six GEMM phases switched to the un-aligned epilogue form (no rendezvous barrier around the epilogue, one realign barrier at phase end)
# baseline (speedup 1.0000x reference)
; __device__ __forceinline__ unsigned cvt_pk_bf16(float lo, float hi) { unsigned r; asm volatile("v_cvt_pk_bf16_f32 %0, %1, %2" : "=v"(r) : "v"(lo), "v"(hi)); return r; }
; #define PG8_BAR __builtin_amdgcn_s_barrier()
;     __device__ __forceinline__ void operator()(const i32x4 (&acc)[2][2][4][2], const Unit& u, int wr, int wc, int fr, int fq) const {
;         const int row0 = u.pm * BM + wr * 64 + fr, col0 = wc * 32 + 8 * fq, bcol = u.pn * BM + wc * 32 + 8 * fq;
;         f32x4 db[2][2];
; #pragma unroll
;         for (int bj = 0; bj < 2; ++bj) { db[bj][0] = *(const f32x4*)(DB + bcol + bj * HALF); db[bj][1] = *(const f32x4*)(DB + bcol + bj * HALF + 4); }
;         float rav[2][4];
; #pragma unroll
;         for (int ai = 0; ai < 2; ++ai)
; #pragma unroll
;             for (int m = 0; m < 4; ++m) rav[ai][m] = RA[row0 + ai * HALF + m * 16];
;         __builtin_amdgcn_sched_barrier(0);
; #pragma unroll
;         for (int ai = 0; ai < 2; ++ai)
; #pragma unroll
;             for (int m = 0; m < 4; ++m) { const int row = row0 + ai * HALF + m * 16; const float ra = rav[ai][m];
; #pragma unroll
;                 for (int bj = 0; bj < 2; ++bj) { float v[8];
; #pragma unroll
;                     for (int j = 0; j < 4; ++j) { v[j] = (float)acc[ai][bj][m][0][j] * ra * db[bj][0][j]; v[4 + j] = (float)acc[ai][bj][m][1][j] * ra * db[bj][1][j]; }
;                     u32x4 w; w.x = cvt_pk_bf16(v[0], v[1]); w.y = cvt_pk_bf16(v[2], v[3]); w.z = cvt_pk_bf16(v[4], v[5]); w.w = cvt_pk_bf16(v[6], v[7]);
;                     const int pc = 2 * u.pn + bj, pl = pc < 16 ? pc : (pc < 32 ? 16 + pc : 64 + pc);
;                     *(u32x4*)(O + ((size_t)pl * Mrows + row) * HALF + col0) = w; } }
; template <class Epi, class Sched, bool ALIGN_EPI = false, bool SP2 = false, bool I8 = false>
; __device__ __forceinline__ void gemm_phase(PG8_LAS unsigned char* lds, const Gemm g, const Sched& S, const Epi& E) {
;     ...
;         if constexpr (ALIGN_EPI) { if (wr == 0) PG8_BAR; }
.Lkloop_exit_0:
.LBB0_211:
	v_lshl_or_b32 v116, s60, 8, v176
	v_lshl_add_u32 v182, s61, 8, v174
	v_ashrrev_i32_e32 v117, 31, v116
	v_ashrrev_i32_e32 v183, 31, v182
	v_or_b32_e32 v172, 16, v182
	v_or_b32_e32 v170, 32, v182
	v_or_b32_e32 v168, 48, v182
	v_lshl_add_u64 v[124:125], v[116:117], 2, s[12:13]
	v_lshl_add_u64 v[160:161], v[182:183], 2, s[10:11]
	v_ashrrev_i32_e32 v173, 31, v172
	v_ashrrev_i32_e32 v171, 31, v170
	v_ashrrev_i32_e32 v169, 31, v168
	global_load_dwordx4 v[132:135], v[124:125], off offset:16
	global_load_dwordx4 v[136:139], v[124:125], off
	global_load_dwordx4 v[116:119], v[124:125], off offset:528
	s_nop 0
	global_load_dwordx4 v[124:127], v[124:125], off offset:512
	v_lshl_add_u64 v[162:163], v[172:173], 2, s[10:11]
	v_lshl_add_u64 v[164:165], v[170:171], 2, s[10:11]
	v_lshl_add_u64 v[166:167], v[168:169], 2, s[10:11]
	global_load_dword v184, v[160:161], off
	global_load_dword v185, v[162:163], off
	global_load_dword v186, v[164:165], off
	global_load_dword v187, v[166:167], off
	global_load_dword v181, v[160:161], off offset:512
	global_load_dword v180, v[160:161], off offset:576
	global_load_dword v179, v[160:161], off offset:640
	global_load_dword v178, v[160:161], off offset:704
	v_add_u32_e32 v166, 0x80, v182
	v_add_u32_e32 v164, 0x90, v182
	v_add_u32_e32 v162, 0xa0, v182
	v_add_u32_e32 v160, 0xb0, v182
	v_ashrrev_i32_e32 v167, 31, v166
	v_ashrrev_i32_e32 v165, 31, v164
	v_ashrrev_i32_e32 v163, 31, v162
	v_ashrrev_i32_e32 v161, 31, v160
	v_cvt_f32_i32_e32 v140, v140
	v_cvt_f32_i32_e32 v145, v145
	s_lshl_b32 s17, s60, 1
	v_cvt_f32_i32_e32 v144, v144
	s_waitcnt vmcnt(0)
	v_mul_f32_e32 v140, v184, v140
	v_mul_f32_e32 v188, v132, v140
	v_cvt_f32_i32_e32 v140, v141
	v_mul_f32_e32 v141, v184, v145
	v_cvt_f32_i32_e32 v145, v146
	s_cmp_lt_i32 s60, 16
	v_mul_f32_e32 v140, v184, v140
	v_mul_f32_e32 v146, v133, v140
	v_cvt_f32_i32_e32 v140, v142
	v_mul_f32_e32 v142, v184, v145
	v_cvt_f32_i32_e32 v145, v147
	v_cvt_f32_i32_e32 v143, v143
	s_cselect_b32 s19, 16, 64
	s_cmp_gt_i32 s60, 7
	s_cselect_b32 s19, s19, 0
	v_mul_f32_e32 v140, v184, v140
	s_add_i32 s26, s19, s17
	v_mul_f32_e32 v144, v184, v144
	v_mul_f32_e32 v147, v134, v140
	v_mul_f32_e32 v140, v184, v145
	s_ashr_i32 s27, s26, 31
	v_cvt_f32_i32_e32 v120, v120
	v_mul_f32_e32 v144, v136, v144
	v_mul_f32_e32 v141, v137, v141
	v_mul_f32_e32 v145, v139, v140
	v_mul_f32_e32 v140, v184, v143
	s_lshl_b64 s[26:27], s[26:27], 14
	v_mul_f32_e32 v142, v138, v142
	v_mul_f32_e32 v143, v135, v140
	v_cvt_pk_bf16_f32 v140, v144, v141
	v_cvt_pk_bf16_f32 v141, v142, v145
	v_lshl_add_u64 v[144:145], s[26:27], 0, v[182:183]
	v_lshlrev_b64 v[144:145], 8, v[144:145]
	v_cvt_f32_i32_e32 v129, v129
	v_lshl_add_u64 v[144:145], v[154:155], 0, v[144:145]
	v_mul_f32_e32 v120, v184, v120
	v_cvt_pk_bf16_f32 v142, v188, v146
	v_cvt_pk_bf16_f32 v143, v147, v143
	global_store_dwordx4 v[144:145], v[140:143], off
	s_or_b32 s17, s17, 1
	v_cvt_f32_i32_e32 v128, v128
	v_mul_f32_e32 v140, v116, v120
	v_cvt_f32_i32_e32 v120, v121
	v_mul_f32_e32 v121, v184, v129
	v_cvt_f32_i32_e32 v129, v130
	s_cmp_lt_i32 s17, 32
	v_mul_f32_e32 v120, v184, v120
	v_mul_f32_e32 v130, v117, v120
	v_cvt_f32_i32_e32 v120, v122
	v_mul_f32_e32 v122, v184, v129
	v_cvt_f32_i32_e32 v129, v131
	v_cvt_f32_i32_e32 v123, v123
	s_cselect_b32 s19, 16, 64
	s_cmp_gt_i32 s17, 15
	s_cselect_b32 s19, s19, 0
	v_mul_f32_e32 v120, v184, v120
	s_add_i32 s36, s19, s17
	v_mul_f32_e32 v128, v184, v128
	v_mul_f32_e32 v131, v118, v120
	v_mul_f32_e32 v120, v184, v129
	s_ashr_i32 s37, s36, 31
	v_cvt_f32_i32_e32 v108, v108
	v_mul_f32_e32 v128, v124, v128
	v_mul_f32_e32 v121, v125, v121
	v_mul_f32_e32 v129, v127, v120
	v_mul_f32_e32 v120, v184, v123
	s_lshl_b64 s[36:37], s[36:37], 14
	v_mul_f32_e32 v122, v126, v122
	v_mul_f32_e32 v123, v119, v120
	v_cvt_pk_bf16_f32 v120, v128, v121
	v_cvt_pk_bf16_f32 v121, v122, v129
	v_lshl_add_u64 v[128:129], s[36:37], 0, v[182:183]
	v_lshlrev_b64 v[128:129], 8, v[128:129]
	v_cvt_f32_i32_e32 v113, v113
	v_lshl_add_u64 v[128:129], v[154:155], 0, v[128:129]
	v_mul_f32_e32 v108, v185, v108
	v_cvt_pk_bf16_f32 v122, v140, v130
	v_cvt_pk_bf16_f32 v123, v131, v123
	global_store_dwordx4 v[128:129], v[120:123], off
	v_cvt_f32_i32_e32 v112, v112
	v_cvt_f32_i32_e32 v111, v111
	v_mul_f32_e32 v120, v132, v108
	v_cvt_f32_i32_e32 v108, v109
	v_mul_f32_e32 v109, v185, v113
	v_cvt_f32_i32_e32 v113, v114
	v_mul_f32_e32 v112, v185, v112
	v_mul_f32_e32 v108, v185, v108
	v_mul_f32_e32 v114, v133, v108
	v_cvt_f32_i32_e32 v108, v110
	v_mul_f32_e32 v110, v185, v113
	v_cvt_f32_i32_e32 v113, v115
	v_cvt_f32_i32_e32 v100, v100
	v_mul_f32_e32 v108, v185, v108
	v_mul_f32_e32 v115, v134, v108
	v_mul_f32_e32 v108, v185, v113
	v_mul_f32_e32 v112, v136, v112
	v_mul_f32_e32 v109, v137, v109
	v_mul_f32_e32 v113, v139, v108
	v_mul_f32_e32 v108, v185, v111
	v_mul_f32_e32 v110, v138, v110
	v_mul_f32_e32 v111, v135, v108
	v_cvt_pk_bf16_f32 v108, v112, v109
	v_cvt_pk_bf16_f32 v109, v110, v113
	v_lshl_add_u64 v[112:113], s[26:27], 0, v[172:173]
	v_lshlrev_b64 v[112:113], 8, v[112:113]
	v_cvt_f32_i32_e32 v105, v105
	v_lshl_add_u64 v[112:113], v[154:155], 0, v[112:113]
	v_mul_f32_e32 v100, v185, v100
	v_cvt_pk_bf16_f32 v110, v120, v114
	v_cvt_pk_bf16_f32 v111, v115, v111
	global_store_dwordx4 v[112:113], v[108:111], off
	v_cvt_f32_i32_e32 v104, v104
	v_cvt_f32_i32_e32 v103, v103
	v_mul_f32_e32 v108, v116, v100
	v_cvt_f32_i32_e32 v100, v101
	v_mul_f32_e32 v101, v185, v105
	v_cvt_f32_i32_e32 v105, v106
	v_mul_f32_e32 v104, v185, v104
	v_mul_f32_e32 v100, v185, v100
	v_mul_f32_e32 v106, v117, v100
	v_cvt_f32_i32_e32 v100, v102
	v_mul_f32_e32 v102, v185, v105
; __device__ __forceinline__ unsigned cvt_pk_bf16(float lo, float hi) { unsigned r; asm volatile("v_cvt_pk_bf16_f32 %0, %1, %2" : "=v"(r) : "v"(lo), "v"(hi)); return r; }
;     __device__ __forceinline__ void operator()(const i32x4 (&acc)[2][2][4][2], const Unit& u, int wr, int wc, int fr, int fq) const {
;     ...
;         for (int ai = 0; ai < 2; ++ai)
; #pragma unroll
;             for (int m = 0; m < 4; ++m) { const int row = row0 + ai * HALF + m * 16; const float ra = rav[ai][m];
; #pragma unroll
;                 for (int bj = 0; bj < 2; ++bj) { float v[8];
; #pragma unroll
;                     for (int j = 0; j < 4; ++j) { v[j] = (float)acc[ai][bj][m][0][j] * ra * db[bj][0][j]; v[4 + j] = (float)acc[ai][bj][m][1][j] * ra * db[bj][1][j]; }
;                     u32x4 w; w.x = cvt_pk_bf16(v[0], v[1]); w.y = cvt_pk_bf16(v[2], v[3]); w.z = cvt_pk_bf16(v[4], v[5]); w.w = cvt_pk_bf16(v[6], v[7]);
;                     const int pc = 2 * u.pn + bj, pl = pc < 16 ? pc : (pc < 32 ? 16 + pc : 64 + pc);
;                     *(u32x4*)(O + ((size_t)pl * Mrows + row) * HALF + col0) = w; } }
	v_cvt_f32_i32_e32 v105, v107
	v_cvt_f32_i32_e32 v92, v92
	v_mul_f32_e32 v100, v185, v100
	v_mul_f32_e32 v107, v118, v100
	v_mul_f32_e32 v100, v185, v105
	v_mul_f32_e32 v104, v124, v104
	v_mul_f32_e32 v101, v125, v101
	v_mul_f32_e32 v105, v127, v100
	v_mul_f32_e32 v100, v185, v103
	v_mul_f32_e32 v102, v126, v102
	v_mul_f32_e32 v103, v119, v100
	v_cvt_pk_bf16_f32 v100, v104, v101
	v_cvt_pk_bf16_f32 v101, v102, v105
	v_lshl_add_u64 v[104:105], s[36:37], 0, v[172:173]
	v_lshlrev_b64 v[104:105], 8, v[104:105]
	v_cvt_f32_i32_e32 v97, v97
	v_lshl_add_u64 v[104:105], v[154:155], 0, v[104:105]
	v_mul_f32_e32 v92, v186, v92
	v_cvt_pk_bf16_f32 v102, v108, v106
	v_cvt_pk_bf16_f32 v103, v107, v103
	global_store_dwordx4 v[104:105], v[100:103], off
	v_cvt_f32_i32_e32 v96, v96
	v_cvt_f32_i32_e32 v95, v95
	v_mul_f32_e32 v100, v132, v92
	v_cvt_f32_i32_e32 v92, v93
	v_mul_f32_e32 v93, v186, v97
	v_cvt_f32_i32_e32 v97, v98
	v_mul_f32_e32 v96, v186, v96
	v_mul_f32_e32 v92, v186, v92
	v_mul_f32_e32 v98, v133, v92
	v_cvt_f32_i32_e32 v92, v94
	v_mul_f32_e32 v94, v186, v97
	v_cvt_f32_i32_e32 v97, v99
	v_cvt_f32_i32_e32 v84, v84
	v_mul_f32_e32 v92, v186, v92
	v_mul_f32_e32 v99, v134, v92
	v_mul_f32_e32 v92, v186, v97
	v_mul_f32_e32 v96, v136, v96
	v_mul_f32_e32 v93, v137, v93
	v_mul_f32_e32 v97, v139, v92
	v_mul_f32_e32 v92, v186, v95
	v_mul_f32_e32 v94, v138, v94
	v_mul_f32_e32 v95, v135, v92
	v_cvt_pk_bf16_f32 v92, v96, v93
	v_cvt_pk_bf16_f32 v93, v94, v97
	v_lshl_add_u64 v[96:97], s[26:27], 0, v[170:171]
	v_lshlrev_b64 v[96:97], 8, v[96:97]
	v_cvt_f32_i32_e32 v89, v89
	v_lshl_add_u64 v[96:97], v[154:155], 0, v[96:97]
	v_mul_f32_e32 v84, v186, v84
	v_cvt_pk_bf16_f32 v94, v100, v98
	v_cvt_pk_bf16_f32 v95, v99, v95
	global_store_dwordx4 v[96:97], v[92:95], off
	v_cvt_f32_i32_e32 v88, v88
	v_cvt_f32_i32_e32 v87, v87
	v_mul_f32_e32 v92, v116, v84
	v_cvt_f32_i32_e32 v84, v85
	v_mul_f32_e32 v85, v186, v89
	v_cvt_f32_i32_e32 v89, v90
	v_mul_f32_e32 v88, v186, v88
	v_mul_f32_e32 v84, v186, v84
	v_mul_f32_e32 v90, v117, v84
	v_cvt_f32_i32_e32 v84, v86
	v_mul_f32_e32 v86, v186, v89
	v_cvt_f32_i32_e32 v89, v91
	v_cvt_f32_i32_e32 v76, v76
	v_mul_f32_e32 v84, v186, v84
	v_mul_f32_e32 v91, v118, v84
	v_mul_f32_e32 v84, v186, v89
	v_mul_f32_e32 v88, v124, v88
	v_mul_f32_e32 v85, v125, v85
	v_mul_f32_e32 v89, v127, v84
	v_mul_f32_e32 v84, v186, v87
	v_mul_f32_e32 v86, v126, v86
	v_mul_f32_e32 v87, v119, v84
	v_cvt_pk_bf16_f32 v84, v88, v85
	v_cvt_pk_bf16_f32 v85, v86, v89
	v_lshl_add_u64 v[88:89], s[36:37], 0, v[170:171]
	v_lshlrev_b64 v[88:89], 8, v[88:89]
	v_cvt_f32_i32_e32 v81, v81
	v_lshl_add_u64 v[88:89], v[154:155], 0, v[88:89]
	v_mul_f32_e32 v76, v187, v76
	v_cvt_pk_bf16_f32 v86, v92, v90
	v_cvt_pk_bf16_f32 v87, v91, v87
	global_store_dwordx4 v[88:89], v[84:87], off
	v_cvt_f32_i32_e32 v80, v80
	v_cvt_f32_i32_e32 v79, v79
	v_mul_f32_e32 v84, v132, v76
	v_cvt_f32_i32_e32 v76, v77
	v_mul_f32_e32 v77, v187, v81
	v_cvt_f32_i32_e32 v81, v82
	v_mul_f32_e32 v80, v187, v80
	v_mul_f32_e32 v76, v187, v76
	v_mul_f32_e32 v82, v133, v76
	v_cvt_f32_i32_e32 v76, v78
	v_mul_f32_e32 v78, v187, v81
	v_cvt_f32_i32_e32 v81, v83
	v_cvt_f32_i32_e32 v68, v68
	v_mul_f32_e32 v76, v187, v76
	v_mul_f32_e32 v83, v134, v76
	v_mul_f32_e32 v76, v187, v81
	v_mul_f32_e32 v80, v136, v80
	v_mul_f32_e32 v77, v137, v77
	v_mul_f32_e32 v81, v139, v76
	v_mul_f32_e32 v76, v187, v79
	v_mul_f32_e32 v78, v138, v78
	v_mul_f32_e32 v79, v135, v76
	v_cvt_pk_bf16_f32 v76, v80, v77
	v_cvt_pk_bf16_f32 v77, v78, v81
	v_lshl_add_u64 v[80:81], s[26:27], 0, v[168:169]
	v_lshlrev_b64 v[80:81], 8, v[80:81]
	v_cvt_f32_i32_e32 v73, v73
	v_lshl_add_u64 v[80:81], v[154:155], 0, v[80:81]
	v_mul_f32_e32 v68, v187, v68
	v_cvt_pk_bf16_f32 v78, v84, v82
	v_cvt_pk_bf16_f32 v79, v83, v79
	global_store_dwordx4 v[80:81], v[76:79], off
	v_cvt_f32_i32_e32 v72, v72
	v_cvt_f32_i32_e32 v71, v71
	v_mul_f32_e32 v76, v116, v68
	v_cvt_f32_i32_e32 v68, v69
	v_mul_f32_e32 v69, v187, v73
	v_cvt_f32_i32_e32 v73, v74
	v_mul_f32_e32 v72, v187, v72
	v_mul_f32_e32 v68, v187, v68
	v_mul_f32_e32 v74, v117, v68
	v_cvt_f32_i32_e32 v68, v70
	v_mul_f32_e32 v70, v187, v73
	v_cvt_f32_i32_e32 v73, v75
	v_cvt_f32_i32_e32 v60, v60
	v_mul_f32_e32 v68, v187, v68
	v_mul_f32_e32 v75, v118, v68
	v_mul_f32_e32 v68, v187, v73
	v_mul_f32_e32 v72, v124, v72
	v_mul_f32_e32 v69, v125, v69
	v_mul_f32_e32 v73, v127, v68
	v_mul_f32_e32 v68, v187, v71
	v_mul_f32_e32 v70, v126, v70
	v_mul_f32_e32 v71, v119, v68
	v_cvt_pk_bf16_f32 v68, v72, v69
	v_cvt_pk_bf16_f32 v69, v70, v73
	v_lshl_add_u64 v[72:73], s[36:37], 0, v[168:169]
	v_lshlrev_b64 v[72:73], 8, v[72:73]
	v_cvt_f32_i32_e32 v65, v65
	v_lshl_add_u64 v[72:73], v[154:155], 0, v[72:73]
	v_mul_f32_e32 v60, v181, v60
	v_cvt_pk_bf16_f32 v70, v76, v74
	v_cvt_pk_bf16_f32 v71, v75, v71
	global_store_dwordx4 v[72:73], v[68:71], off
	v_cvt_f32_i32_e32 v64, v64
	v_cvt_f32_i32_e32 v63, v63
	v_mul_f32_e32 v68, v132, v60
	v_cvt_f32_i32_e32 v60, v61
	v_mul_f32_e32 v61, v181, v65
	v_cvt_f32_i32_e32 v65, v66
	v_mul_f32_e32 v64, v181, v64
	v_mul_f32_e32 v60, v181, v60
	v_mul_f32_e32 v66, v133, v60
	v_cvt_f32_i32_e32 v60, v62
	v_mul_f32_e32 v62, v181, v65
	v_cvt_f32_i32_e32 v65, v67
	v_cvt_f32_i32_e32 v52, v52
	v_mul_f32_e32 v60, v181, v60
	v_mul_f32_e32 v67, v134, v60
	v_mul_f32_e32 v60, v181, v65
	v_mul_f32_e32 v64, v136, v64
	v_mul_f32_e32 v61, v137, v61
	v_mul_f32_e32 v65, v139, v60
	v_mul_f32_e32 v60, v181, v63
	v_mul_f32_e32 v62, v138, v62
	v_mul_f32_e32 v63, v135, v60
	v_cvt_pk_bf16_f32 v60, v64, v61
	v_cvt_pk_bf16_f32 v61, v62, v65
	v_lshl_add_u64 v[64:65], s[26:27], 0, v[166:167]
	v_lshlrev_b64 v[64:65], 8, v[64:65]
	v_cvt_f32_i32_e32 v57, v57
; __device__ __forceinline__ unsigned cvt_pk_bf16(float lo, float hi) { unsigned r; asm volatile("v_cvt_pk_bf16_f32 %0, %1, %2" : "=v"(r) : "v"(lo), "v"(hi)); return r; }
;     __device__ __forceinline__ void operator()(const i32x4 (&acc)[2][2][4][2], const Unit& u, int wr, int wc, int fr, int fq) const {
;     ...
;         for (int ai = 0; ai < 2; ++ai)
; #pragma unroll
;             for (int m = 0; m < 4; ++m) { const int row = row0 + ai * HALF + m * 16; const float ra = rav[ai][m];
; #pragma unroll
;                 for (int bj = 0; bj < 2; ++bj) { float v[8];
; #pragma unroll
;                     for (int j = 0; j < 4; ++j) { v[j] = (float)acc[ai][bj][m][0][j] * ra * db[bj][0][j]; v[4 + j] = (float)acc[ai][bj][m][1][j] * ra * db[bj][1][j]; }
;                     u32x4 w; w.x = cvt_pk_bf16(v[0], v[1]); w.y = cvt_pk_bf16(v[2], v[3]); w.z = cvt_pk_bf16(v[4], v[5]); w.w = cvt_pk_bf16(v[6], v[7]);
;                     const int pc = 2 * u.pn + bj, pl = pc < 16 ? pc : (pc < 32 ? 16 + pc : 64 + pc);
;                     *(u32x4*)(O + ((size_t)pl * Mrows + row) * HALF + col0) = w; } }
	v_lshl_add_u64 v[64:65], v[154:155], 0, v[64:65]
	v_mul_f32_e32 v52, v181, v52
	v_cvt_pk_bf16_f32 v62, v68, v66
	v_cvt_pk_bf16_f32 v63, v67, v63
	global_store_dwordx4 v[64:65], v[60:63], off
	v_cvt_f32_i32_e32 v56, v56
	v_cvt_f32_i32_e32 v55, v55
	v_mul_f32_e32 v60, v116, v52
	v_cvt_f32_i32_e32 v52, v53
	v_mul_f32_e32 v53, v181, v57
	v_cvt_f32_i32_e32 v57, v58
	v_mul_f32_e32 v56, v181, v56
	v_mul_f32_e32 v52, v181, v52
	v_mul_f32_e32 v58, v117, v52
	v_cvt_f32_i32_e32 v52, v54
	v_mul_f32_e32 v54, v181, v57
	v_cvt_f32_i32_e32 v57, v59
	v_cvt_f32_i32_e32 v44, v44
	v_mul_f32_e32 v52, v181, v52
	v_mul_f32_e32 v59, v118, v52
	v_mul_f32_e32 v52, v181, v57
	v_mul_f32_e32 v56, v124, v56
	v_mul_f32_e32 v53, v125, v53
	v_mul_f32_e32 v57, v127, v52
	v_mul_f32_e32 v52, v181, v55
	v_mul_f32_e32 v54, v126, v54
	v_mul_f32_e32 v55, v119, v52
	v_cvt_pk_bf16_f32 v52, v56, v53
	v_cvt_pk_bf16_f32 v53, v54, v57
	v_lshl_add_u64 v[56:57], s[36:37], 0, v[166:167]
	v_lshlrev_b64 v[56:57], 8, v[56:57]
	v_cvt_f32_i32_e32 v49, v49
	v_lshl_add_u64 v[56:57], v[154:155], 0, v[56:57]
	v_mul_f32_e32 v44, v180, v44
	v_cvt_pk_bf16_f32 v54, v60, v58
	v_cvt_pk_bf16_f32 v55, v59, v55
	global_store_dwordx4 v[56:57], v[52:55], off
	v_cvt_f32_i32_e32 v48, v48
	v_cvt_f32_i32_e32 v47, v47
	v_mul_f32_e32 v52, v132, v44
	v_cvt_f32_i32_e32 v44, v45
	v_mul_f32_e32 v45, v180, v49
	v_cvt_f32_i32_e32 v49, v50
	v_mul_f32_e32 v48, v180, v48
	v_mul_f32_e32 v44, v180, v44
	v_mul_f32_e32 v50, v133, v44
	v_cvt_f32_i32_e32 v44, v46
	v_mul_f32_e32 v46, v180, v49
	v_cvt_f32_i32_e32 v49, v51
	v_cvt_f32_i32_e32 v36, v36
	v_mul_f32_e32 v44, v180, v44
	v_mul_f32_e32 v51, v134, v44
	v_mul_f32_e32 v44, v180, v49
	v_mul_f32_e32 v48, v136, v48
	v_mul_f32_e32 v45, v137, v45
	v_mul_f32_e32 v49, v139, v44
	v_mul_f32_e32 v44, v180, v47
	v_mul_f32_e32 v46, v138, v46
	v_mul_f32_e32 v47, v135, v44
	v_cvt_pk_bf16_f32 v44, v48, v45
	v_cvt_pk_bf16_f32 v45, v46, v49
	v_lshl_add_u64 v[48:49], s[26:27], 0, v[164:165]
	v_lshlrev_b64 v[48:49], 8, v[48:49]
	v_cvt_f32_i32_e32 v41, v41
	v_lshl_add_u64 v[48:49], v[154:155], 0, v[48:49]
	v_mul_f32_e32 v36, v180, v36
	v_cvt_pk_bf16_f32 v46, v52, v50
	v_cvt_pk_bf16_f32 v47, v51, v47
	global_store_dwordx4 v[48:49], v[44:47], off
	v_cvt_f32_i32_e32 v40, v40
	v_cvt_f32_i32_e32 v39, v39
	v_mul_f32_e32 v44, v116, v36
	v_cvt_f32_i32_e32 v36, v37
	v_mul_f32_e32 v37, v180, v41
	v_cvt_f32_i32_e32 v41, v42
	v_mul_f32_e32 v40, v180, v40
	v_mul_f32_e32 v36, v180, v36
	v_mul_f32_e32 v42, v117, v36
	v_cvt_f32_i32_e32 v36, v38
	v_mul_f32_e32 v38, v180, v41
	v_cvt_f32_i32_e32 v41, v43
	v_cvt_f32_i32_e32 v28, v28
	v_mul_f32_e32 v36, v180, v36
	v_mul_f32_e32 v43, v118, v36
	v_mul_f32_e32 v36, v180, v41
	v_mul_f32_e32 v40, v124, v40
	v_mul_f32_e32 v37, v125, v37
	v_mul_f32_e32 v41, v127, v36
	v_mul_f32_e32 v36, v180, v39
	v_mul_f32_e32 v38, v126, v38
	v_mul_f32_e32 v39, v119, v36
	v_cvt_pk_bf16_f32 v36, v40, v37
	v_cvt_pk_bf16_f32 v37, v38, v41
	v_lshl_add_u64 v[40:41], s[36:37], 0, v[164:165]
	v_lshlrev_b64 v[40:41], 8, v[40:41]
	v_cvt_f32_i32_e32 v33, v33
	v_lshl_add_u64 v[40:41], v[154:155], 0, v[40:41]
	v_mul_f32_e32 v28, v179, v28
	v_cvt_pk_bf16_f32 v38, v44, v42
	v_cvt_pk_bf16_f32 v39, v43, v39
	global_store_dwordx4 v[40:41], v[36:39], off
	v_cvt_f32_i32_e32 v32, v32
	v_cvt_f32_i32_e32 v31, v31
	v_mul_f32_e32 v36, v132, v28
	v_cvt_f32_i32_e32 v28, v29
	v_mul_f32_e32 v29, v179, v33
	v_cvt_f32_i32_e32 v33, v34
	v_mul_f32_e32 v32, v179, v32
	v_mul_f32_e32 v28, v179, v28
	v_mul_f32_e32 v34, v133, v28
	v_cvt_f32_i32_e32 v28, v30
	v_mul_f32_e32 v30, v179, v33
	v_cvt_f32_i32_e32 v33, v35
	v_cvt_f32_i32_e32 v20, v20
	v_mul_f32_e32 v28, v179, v28
	v_mul_f32_e32 v35, v134, v28
	v_mul_f32_e32 v28, v179, v33
	v_mul_f32_e32 v32, v136, v32
	v_mul_f32_e32 v29, v137, v29
	v_mul_f32_e32 v33, v139, v28
	v_mul_f32_e32 v28, v179, v31
	v_mul_f32_e32 v30, v138, v30
	v_mul_f32_e32 v31, v135, v28
	v_cvt_pk_bf16_f32 v28, v32, v29
	v_cvt_pk_bf16_f32 v29, v30, v33
; __device__ __forceinline__ unsigned cvt_pk_bf16(float lo, float hi) { unsigned r; asm volatile("v_cvt_pk_bf16_f32 %0, %1, %2" : "=v"(r) : "v"(lo), "v"(hi)); return r; }
; #define PG8_WAIT_V(n) asm volatile("s_waitcnt vmcnt(" #n ")" ::: "memory")
; #define PG8_BAR __builtin_amdgcn_s_barrier()
;     __device__ __forceinline__ void operator()(const i32x4 (&acc)[2][2][4][2], const Unit& u, int wr, int wc, int fr, int fq) const {
;     ...
;         for (int ai = 0; ai < 2; ++ai)
; #pragma unroll
;             for (int m = 0; m < 4; ++m) { const int row = row0 + ai * HALF + m * 16; const float ra = rav[ai][m];
; #pragma unroll
;                 for (int bj = 0; bj < 2; ++bj) { float v[8];
; #pragma unroll
;                     for (int j = 0; j < 4; ++j) { v[j] = (float)acc[ai][bj][m][0][j] * ra * db[bj][0][j]; v[4 + j] = (float)acc[ai][bj][m][1][j] * ra * db[bj][1][j]; }
;                     u32x4 w; w.x = cvt_pk_bf16(v[0], v[1]); w.y = cvt_pk_bf16(v[2], v[3]); w.z = cvt_pk_bf16(v[4], v[5]); w.w = cvt_pk_bf16(v[6], v[7]);
;                     const int pc = 2 * u.pn + bj, pl = pc < 16 ? pc : (pc < 32 ? 16 + pc : 64 + pc);
;                     *(u32x4*)(O + ((size_t)pl * Mrows + row) * HALF + col0) = w; } }
; template <class Epi, class Sched, bool ALIGN_EPI = false, bool SP2 = false, bool I8 = false>
; __device__ __forceinline__ void gemm_phase(PG8_LAS unsigned char* lds, const Gemm g, const Sched& S, const Epi& E) {
;     ...
;         cur = nxt; cA = nA; cB = nB; ++ui;
;         if constexpr (ALIGN_EPI) { if (wr == 1) PG8_BAR; }
;     }
;     PG8_WAIT_V(0);
;     if constexpr (!ALIGN_EPI) { if (wr == 0) PG8_BAR; }
;     PG8_BAR;
	v_lshl_add_u64 v[32:33], s[26:27], 0, v[162:163]
	v_lshlrev_b64 v[32:33], 8, v[32:33]
	v_cvt_f32_i32_e32 v25, v25
	v_lshl_add_u64 v[32:33], v[154:155], 0, v[32:33]
	v_mul_f32_e32 v20, v179, v20
	v_cvt_pk_bf16_f32 v30, v36, v34
	v_cvt_pk_bf16_f32 v31, v35, v31
	global_store_dwordx4 v[32:33], v[28:31], off
	v_cvt_f32_i32_e32 v24, v24
	v_cvt_f32_i32_e32 v23, v23
	v_mul_f32_e32 v28, v116, v20
	v_cvt_f32_i32_e32 v20, v21
	v_mul_f32_e32 v21, v179, v25
	v_cvt_f32_i32_e32 v25, v26
	v_mul_f32_e32 v24, v179, v24
	v_mul_f32_e32 v20, v179, v20
	v_mul_f32_e32 v26, v117, v20
	v_cvt_f32_i32_e32 v20, v22
	v_mul_f32_e32 v22, v179, v25
	v_cvt_f32_i32_e32 v25, v27
	v_cvt_f32_i32_e32 v12, v12
	v_mul_f32_e32 v20, v179, v20
	v_mul_f32_e32 v27, v118, v20
	v_mul_f32_e32 v20, v179, v25
	v_mul_f32_e32 v24, v124, v24
	v_mul_f32_e32 v21, v125, v21
	v_mul_f32_e32 v25, v127, v20
	v_mul_f32_e32 v20, v179, v23
	v_mul_f32_e32 v22, v126, v22
	v_mul_f32_e32 v23, v119, v20
	v_cvt_pk_bf16_f32 v20, v24, v21
	v_cvt_pk_bf16_f32 v21, v22, v25
	v_lshl_add_u64 v[24:25], s[36:37], 0, v[162:163]
	v_lshlrev_b64 v[24:25], 8, v[24:25]
	v_cvt_f32_i32_e32 v17, v17
	v_lshl_add_u64 v[24:25], v[154:155], 0, v[24:25]
	v_mul_f32_e32 v12, v178, v12
	v_cvt_pk_bf16_f32 v22, v28, v26
	v_cvt_pk_bf16_f32 v23, v27, v23
	global_store_dwordx4 v[24:25], v[20:23], off
	v_cvt_f32_i32_e32 v16, v16
	v_cvt_f32_i32_e32 v15, v15
	v_mul_f32_e32 v20, v132, v12
	v_cvt_f32_i32_e32 v12, v13
	v_mul_f32_e32 v13, v178, v17
	v_cvt_f32_i32_e32 v17, v18
	v_mul_f32_e32 v16, v178, v16
	v_mul_f32_e32 v12, v178, v12
	v_mul_f32_e32 v18, v133, v12
	v_cvt_f32_i32_e32 v12, v14
	v_mul_f32_e32 v14, v178, v17
	v_cvt_f32_i32_e32 v17, v19
	v_cvt_f32_i32_e32 v4, v4
	v_mul_f32_e32 v12, v178, v12
	v_mul_f32_e32 v19, v134, v12
	v_mul_f32_e32 v12, v178, v17
	v_mul_f32_e32 v16, v136, v16
	v_mul_f32_e32 v13, v137, v13
	v_mul_f32_e32 v17, v139, v12
	v_mul_f32_e32 v12, v178, v15
	v_mul_f32_e32 v14, v138, v14
	v_mul_f32_e32 v15, v135, v12
	v_cvt_pk_bf16_f32 v12, v16, v13
	v_cvt_pk_bf16_f32 v13, v14, v17
	v_lshl_add_u64 v[16:17], s[26:27], 0, v[160:161]
	v_lshlrev_b64 v[16:17], 8, v[16:17]
	v_cvt_f32_i32_e32 v9, v9
	v_lshl_add_u64 v[16:17], v[154:155], 0, v[16:17]
	v_mul_f32_e32 v4, v178, v4
	v_cvt_pk_bf16_f32 v14, v20, v18
	v_cvt_pk_bf16_f32 v15, v19, v15
	global_store_dwordx4 v[16:17], v[12:15], off
	v_cvt_f32_i32_e32 v8, v8
	v_cvt_f32_i32_e32 v7, v7
	v_mul_f32_e32 v12, v116, v4
	v_cvt_f32_i32_e32 v4, v5
	v_mul_f32_e32 v5, v178, v9
	v_cvt_f32_i32_e32 v9, v10
	v_mul_f32_e32 v8, v178, v8
	v_mul_f32_e32 v4, v178, v4
	v_mul_f32_e32 v10, v117, v4
	v_cvt_f32_i32_e32 v4, v6
	v_mul_f32_e32 v6, v178, v9
	v_cvt_f32_i32_e32 v9, v11
	v_mul_f32_e32 v8, v124, v8
	v_mul_f32_e32 v4, v178, v4
	v_mul_f32_e32 v11, v118, v4
	v_mul_f32_e32 v4, v178, v9
	v_mul_f32_e32 v5, v125, v5
	v_mul_f32_e32 v9, v127, v4
	v_mul_f32_e32 v4, v178, v7
	v_mul_f32_e32 v6, v126, v6
	v_mul_f32_e32 v7, v119, v4
	v_cvt_pk_bf16_f32 v4, v8, v5
	v_cvt_pk_bf16_f32 v5, v6, v9
	v_lshl_add_u64 v[8:9], s[36:37], 0, v[160:161]
	v_lshlrev_b64 v[8:9], 8, v[8:9]
	v_lshl_add_u64 v[8:9], v[154:155], 0, v[8:9]
	s_andn2_b64 vcc, exec, s[6:7]
	s_mov_b64 s[6:7], -1
	v_cvt_pk_bf16_f32 v6, v12, v10
	v_cvt_pk_bf16_f32 v7, v11, v7
	global_store_dwordx4 v[8:9], v[4:7], off
	s_cbranch_vccnz .LBB0_204
	s_andn2_b64 vcc, exec, s[8:9]
	s_cbranch_vccnz .LBB0_203
	s_branch .LBB0_203
.LBB0_214:
	s_waitcnt vmcnt(0)
	s_and_b64 vcc, exec, s[14:15]
	s_cbranch_vccz .Lnoalign_0
	s_barrier
.Lnoalign_0:
	s_barrier
.LBB0_215:
	v_readlane_b32 s6, v254, 0
	v_readlane_b32 s7, v254, 1
	s_load_dwordx2 s[8:9], s[6:7], 0x98
	s_load_dwordx4 s[16:19], s[6:7], 0x40
	v_readlane_b32 s10, v254, 9
	v_readlane_b32 s11, v254, 10
	v_mov_b32_e32 v18, v0
	s_andn2_b64 vcc, exec, s[10:11]
	v_cndmask_b32_e64 v2, 0, 1, s[10:11]
	v_cmp_ne_u32_e64 s[6:7], 1, v2
	v_readfirstlane_b32 s24, v18
	s_cbranch_vccnz .LBB0_217
	v_readlane_b32 s10, v254, 27
	s_mov_b32 s60, s10
	v_readlane_b32 s10, v254, 28

; __device__ __forceinline__ unsigned cvt_pk_bf16(float lo, float hi) { unsigned r; asm volatile("v_cvt_pk_bf16_f32 %0, %1, %2" : "=v"(r) : "v"(lo), "v"(hi)); return r; }
;     __device__ __forceinline__ void operator()(const f32x4 (&acc)[2][2][4][2], const Unit& u, int wr, int wc, int fr, int fq) const {
;         const int row0 = u.pm * BM + wr * 64 + fr, col0 = u.pn * BM + wc * 32 + 8 * fq;
;         u32x4 xv[2][4][2];
; #pragma unroll
;         for (int ai = 0; ai < 2; ++ai)
; #pragma unroll
;             for (int m = 0; m < 4; ++m)
; #pragma unroll
;                 for (int bj = 0; bj < 2; ++bj) xv[ai][m][bj] = *(const u32x4*)(XB + (size_t)(row0 + ai * HALF + m * 16) * ldc + col0 + bj * HALF);
; #pragma unroll
;         for (int ai = 0; ai < 2; ++ai) {
; #pragma unroll
;             for (int m = 0; m < 4; ++m) { const int row = row0 + ai * HALF + m * 16;
; #pragma unroll
;                 for (int bj = 0; bj < 2; ++bj) { f32x4 v0, v1; unpack8(xv[ai][m][bj], v0, v1); v0 = v0 + acc[ai][bj][m][0]; v1 = v1 + acc[ai][bj][m][1];
;                     u32x4 w; w.x = cvt_pk_bf16(v0[0], v0[1]); w.y = cvt_pk_bf16(v0[2], v0[3]); w.z = cvt_pk_bf16(v1[0], v1[1]); w.w = cvt_pk_bf16(v1[2], v1[3]);
;                     *(u32x4*)(XB + (size_t)row * ldc + col0 + bj * HALF) = w; } }
.Lkloop_exit_2:
.LBB0_1459:
	v_lshl_or_b32 v126, s49, 8, v241
	v_lshl_add_u32 v124, s50, 8, v239
	v_ashrrev_i32_e32 v127, 31, v126
	v_lshlrev_b64 v[214:215], 1, v[126:127]
	v_ashrrev_i32_e32 v125, 31, v124
	v_lshl_add_u64 v[126:127], s[12:13], 0, v[214:215]
	v_lshlrev_b64 v[248:249], 13, v[124:125]
	v_lshl_add_u64 v[128:129], v[126:127], 0, v[248:249]
	global_load_dwordx4 v[244:247], v[128:129], off
	global_load_dwordx4 v[188:191], v[128:129], off offset:256
	v_or_b32_e32 v128, 16, v124
	v_ashrrev_i32_e32 v129, 31, v128
	v_lshlrev_b64 v[228:229], 13, v[128:129]
	v_lshl_add_u64 v[128:129], v[126:127], 0, v[228:229]
	global_load_dwordx4 v[184:187], v[128:129], off
	global_load_dwordx4 v[180:183], v[128:129], off offset:256
	v_or_b32_e32 v128, 32, v124
	v_ashrrev_i32_e32 v129, 31, v128
	v_lshlrev_b64 v[226:227], 13, v[128:129]
	v_lshl_add_u64 v[128:129], v[126:127], 0, v[226:227]
	global_load_dwordx4 v[176:179], v[128:129], off
	global_load_dwordx4 v[168:171], v[128:129], off offset:256
	v_or_b32_e32 v124, 48, v124
	v_ashrrev_i32_e32 v125, 31, v124
	v_lshlrev_b64 v[224:225], 13, v[124:125]
	v_lshl_add_u64 v[124:125], v[126:127], 0, v[224:225]
	global_load_dwordx4 v[172:175], v[124:125], off
	global_load_dwordx4 v[164:167], v[124:125], off offset:256
	s_mov_b64 s[24:25], 0x100000
	v_lshl_add_u64 v[222:223], v[248:249], 0, s[24:25]
	v_lshl_add_u64 v[124:125], v[126:127], 0, v[222:223]
	global_load_dwordx4 v[160:163], v[124:125], off
	global_load_dwordx4 v[156:159], v[124:125], off offset:256
	s_mov_b64 s[24:25], 0x120000
	v_lshl_add_u64 v[220:221], v[248:249], 0, s[24:25]
	v_lshl_add_u64 v[124:125], v[126:127], 0, v[220:221]
	global_load_dwordx4 v[152:155], v[124:125], off
	global_load_dwordx4 v[148:151], v[124:125], off offset:256
	s_mov_b64 s[24:25], 0x140000
	v_lshl_add_u64 v[218:219], v[248:249], 0, s[24:25]
	v_lshl_add_u64 v[124:125], v[126:127], 0, v[218:219]
	global_load_dwordx4 v[144:147], v[124:125], off
	global_load_dwordx4 v[132:135], v[124:125], off offset:256
	s_mov_b64 s[24:25], 0x160000
	v_lshl_add_u64 v[216:217], v[248:249], 0, s[24:25]
	v_lshl_add_u64 v[124:125], v[126:127], 0, v[216:217]
	global_load_dwordx4 v[128:131], v[124:125], off
	s_nop 0
	global_load_dwordx4 v[124:127], v[124:125], off offset:256
	s_mov_b64 s[24:25], -1
	s_andn2_b64 vcc, exec, s[8:9]
	s_waitcnt vmcnt(0)
	v_lshlrev_b32_e32 v250, 16, v244
	v_and_b32_e32 v251, 0xffff0000, v244
	v_lshlrev_b32_e32 v244, 16, v245
	v_and_b32_e32 v245, 0xffff0000, v245
	v_lshlrev_b32_e32 v252, 16, v246
	v_and_b32_e32 v253, 0xffff0000, v246
	v_lshlrev_b32_e32 v246, 16, v247
	v_and_b32_e32 v247, 0xffff0000, v247
	v_pk_add_f32 v[140:141], v[140:141], v[250:251]
	v_pk_add_f32 v[142:143], v[142:143], v[244:245]
	v_pk_add_f32 v[244:245], v[138:139], v[246:247]
	v_pk_add_f32 v[138:139], v[136:137], v[252:253]
	v_cvt_pk_bf16_f32 v136, v140, v141
	v_lshl_add_u64 v[140:141], s[12:13], 0, v[248:249]
	v_cvt_pk_bf16_f32 v137, v142, v143
	v_cvt_pk_bf16_f32 v138, v138, v139
	v_cvt_pk_bf16_f32 v139, v244, v245
	v_lshl_add_u64 v[140:141], v[140:141], 0, v[214:215]
	global_store_dwordx4 v[140:141], v[136:139], off
	v_lshlrev_b32_e32 v142, 16, v190
	v_and_b32_e32 v143, 0xffff0000, v190
	v_lshlrev_b32_e32 v136, 16, v188
	v_and_b32_e32 v137, 0xffff0000, v188
	v_lshlrev_b32_e32 v138, 16, v189
	v_and_b32_e32 v139, 0xffff0000, v189
	v_lshlrev_b32_e32 v188, 16, v191
	v_and_b32_e32 v189, 0xffff0000, v191
	v_pk_add_f32 v[122:123], v[122:123], v[138:139]
	v_pk_add_f32 v[120:121], v[120:121], v[136:137]
	v_pk_add_f32 v[136:137], v[118:119], v[188:189]
	v_pk_add_f32 v[118:119], v[116:117], v[142:143]
	v_cvt_pk_bf16_f32 v116, v120, v121
	v_cvt_pk_bf16_f32 v117, v122, v123
	v_lshlrev_b32_e32 v120, 16, v186
	v_cvt_pk_bf16_f32 v118, v118, v119
	v_cvt_pk_bf16_f32 v119, v136, v137
	global_store_dwordx4 v[140:141], v[116:119], off offset:256
	v_and_b32_e32 v121, 0xffff0000, v186
	v_lshlrev_b32_e32 v122, 16, v187
	v_lshlrev_b32_e32 v116, 16, v184
	v_and_b32_e32 v117, 0xffff0000, v184
	v_and_b32_e32 v123, 0xffff0000, v187
	v_pk_add_f32 v[112:113], v[112:113], v[116:117]
	v_lshlrev_b32_e32 v118, 16, v185
	v_and_b32_e32 v119, 0xffff0000, v185
	v_pk_add_f32 v[116:117], v[110:111], v[122:123]
	v_pk_add_f32 v[110:111], v[108:109], v[120:121]
	v_cvt_pk_bf16_f32 v108, v112, v113
	v_lshl_add_u64 v[112:113], s[12:13], 0, v[228:229]
	v_pk_add_f32 v[114:115], v[114:115], v[118:119]
	v_lshl_add_u64 v[112:113], v[112:113], 0, v[214:215]
	v_cvt_pk_bf16_f32 v109, v114, v115
	v_cvt_pk_bf16_f32 v110, v110, v111
	v_cvt_pk_bf16_f32 v111, v116, v117
	global_store_dwordx4 v[112:113], v[108:111], off
	v_lshlrev_b32_e32 v114, 16, v182
	v_and_b32_e32 v115, 0xffff0000, v182
	v_lshlrev_b32_e32 v108, 16, v180
	v_and_b32_e32 v109, 0xffff0000, v180
	v_lshlrev_b32_e32 v110, 16, v181
	v_and_b32_e32 v111, 0xffff0000, v181
	v_lshlrev_b32_e32 v116, 16, v183
	v_and_b32_e32 v117, 0xffff0000, v183
	v_pk_add_f32 v[106:107], v[106:107], v[110:111]
	v_pk_add_f32 v[104:105], v[104:105], v[108:109]
	v_pk_add_f32 v[108:109], v[102:103], v[116:117]
	v_pk_add_f32 v[102:103], v[100:101], v[114:115]
	v_cvt_pk_bf16_f32 v100, v104, v105
	v_cvt_pk_bf16_f32 v101, v106, v107
	v_lshlrev_b32_e32 v104, 16, v178
	v_cvt_pk_bf16_f32 v102, v102, v103
	v_cvt_pk_bf16_f32 v103, v108, v109
	global_store_dwordx4 v[112:113], v[100:103], off offset:256
	v_and_b32_e32 v105, 0xffff0000, v178
	v_lshlrev_b32_e32 v106, 16, v179
	v_lshlrev_b32_e32 v100, 16, v176
	v_and_b32_e32 v101, 0xffff0000, v176
	v_and_b32_e32 v107, 0xffff0000, v179
	v_pk_add_f32 v[96:97], v[96:97], v[100:101]
	v_lshlrev_b32_e32 v102, 16, v177
	v_and_b32_e32 v103, 0xffff0000, v177
	v_pk_add_f32 v[100:101], v[94:95], v[106:107]
; __device__ __forceinline__ unsigned cvt_pk_bf16(float lo, float hi) { unsigned r; asm volatile("v_cvt_pk_bf16_f32 %0, %1, %2" : "=v"(r) : "v"(lo), "v"(hi)); return r; }
;     __device__ __forceinline__ void operator()(const f32x4 (&acc)[2][2][4][2], const Unit& u, int wr, int wc, int fr, int fq) const {
;         const int row0 = u.pm * BM + wr * 64 + fr, col0 = u.pn * BM + wc * 32 + 8 * fq;
;         u32x4 xv[2][4][2];
; #pragma unroll
;         for (int ai = 0; ai < 2; ++ai)
; #pragma unroll
;             for (int m = 0; m < 4; ++m)
; #pragma unroll
;                 for (int bj = 0; bj < 2; ++bj) xv[ai][m][bj] = *(const u32x4*)(XB + (size_t)(row0 + ai * HALF + m * 16) * ldc + col0 + bj * HALF);
; #pragma unroll
;         for (int ai = 0; ai < 2; ++ai) {
; #pragma unroll
;             for (int m = 0; m < 4; ++m) { const int row = row0 + ai * HALF + m * 16;
; #pragma unroll
;                 for (int bj = 0; bj < 2; ++bj) { f32x4 v0, v1; unpack8(xv[ai][m][bj], v0, v1); v0 = v0 + acc[ai][bj][m][0]; v1 = v1 + acc[ai][bj][m][1];
;                     u32x4 w; w.x = cvt_pk_bf16(v0[0], v0[1]); w.y = cvt_pk_bf16(v0[2], v0[3]); w.z = cvt_pk_bf16(v1[0], v1[1]); w.w = cvt_pk_bf16(v1[2], v1[3]);
;                     *(u32x4*)(XB + (size_t)row * ldc + col0 + bj * HALF) = w; } }
	v_pk_add_f32 v[94:95], v[92:93], v[104:105]
	v_cvt_pk_bf16_f32 v92, v96, v97
	v_lshl_add_u64 v[96:97], s[12:13], 0, v[226:227]
	v_pk_add_f32 v[98:99], v[98:99], v[102:103]
	v_lshl_add_u64 v[96:97], v[96:97], 0, v[214:215]
	v_cvt_pk_bf16_f32 v93, v98, v99
	v_cvt_pk_bf16_f32 v94, v94, v95
	v_cvt_pk_bf16_f32 v95, v100, v101
	global_store_dwordx4 v[96:97], v[92:95], off
	v_lshlrev_b32_e32 v98, 16, v170
	v_and_b32_e32 v99, 0xffff0000, v170
	v_lshlrev_b32_e32 v92, 16, v168
	v_and_b32_e32 v93, 0xffff0000, v168
	v_lshlrev_b32_e32 v94, 16, v169
	v_and_b32_e32 v95, 0xffff0000, v169
	v_lshlrev_b32_e32 v100, 16, v171
	v_and_b32_e32 v101, 0xffff0000, v171
	v_pk_add_f32 v[90:91], v[90:91], v[94:95]
	v_pk_add_f32 v[88:89], v[88:89], v[92:93]
	v_pk_add_f32 v[92:93], v[86:87], v[100:101]
	v_pk_add_f32 v[86:87], v[84:85], v[98:99]
	v_cvt_pk_bf16_f32 v84, v88, v89
	v_cvt_pk_bf16_f32 v85, v90, v91
	v_lshlrev_b32_e32 v88, 16, v174
	v_cvt_pk_bf16_f32 v86, v86, v87
	v_cvt_pk_bf16_f32 v87, v92, v93
	global_store_dwordx4 v[96:97], v[84:87], off offset:256
	v_and_b32_e32 v89, 0xffff0000, v174
	v_lshlrev_b32_e32 v90, 16, v175
	v_lshlrev_b32_e32 v84, 16, v172
	v_and_b32_e32 v85, 0xffff0000, v172
	v_and_b32_e32 v91, 0xffff0000, v175
	v_pk_add_f32 v[80:81], v[80:81], v[84:85]
	v_lshlrev_b32_e32 v86, 16, v173
	v_and_b32_e32 v87, 0xffff0000, v173
	v_pk_add_f32 v[84:85], v[78:79], v[90:91]
	v_pk_add_f32 v[78:79], v[76:77], v[88:89]
	v_cvt_pk_bf16_f32 v76, v80, v81
	v_lshl_add_u64 v[80:81], s[12:13], 0, v[224:225]
	v_pk_add_f32 v[82:83], v[82:83], v[86:87]
	v_lshl_add_u64 v[80:81], v[80:81], 0, v[214:215]
	v_cvt_pk_bf16_f32 v77, v82, v83
	v_cvt_pk_bf16_f32 v78, v78, v79
	v_cvt_pk_bf16_f32 v79, v84, v85
	global_store_dwordx4 v[80:81], v[76:79], off
	v_lshlrev_b32_e32 v82, 16, v166
	v_and_b32_e32 v83, 0xffff0000, v166
	v_lshlrev_b32_e32 v76, 16, v164
	v_and_b32_e32 v77, 0xffff0000, v164
	v_lshlrev_b32_e32 v78, 16, v165
	v_and_b32_e32 v79, 0xffff0000, v165
	v_lshlrev_b32_e32 v84, 16, v167
	v_and_b32_e32 v85, 0xffff0000, v167
	v_pk_add_f32 v[74:75], v[74:75], v[78:79]
	v_pk_add_f32 v[72:73], v[72:73], v[76:77]
	v_pk_add_f32 v[76:77], v[70:71], v[84:85]
	v_pk_add_f32 v[70:71], v[68:69], v[82:83]
	v_cvt_pk_bf16_f32 v68, v72, v73
	v_cvt_pk_bf16_f32 v69, v74, v75
	v_lshlrev_b32_e32 v72, 16, v162
	v_cvt_pk_bf16_f32 v70, v70, v71
	v_cvt_pk_bf16_f32 v71, v76, v77
	global_store_dwordx4 v[80:81], v[68:71], off offset:256
	v_and_b32_e32 v73, 0xffff0000, v162
	v_lshlrev_b32_e32 v74, 16, v163
	v_lshlrev_b32_e32 v68, 16, v160
	v_and_b32_e32 v69, 0xffff0000, v160
	v_and_b32_e32 v75, 0xffff0000, v163
	v_pk_add_f32 v[64:65], v[64:65], v[68:69]
	v_lshlrev_b32_e32 v70, 16, v161
	v_and_b32_e32 v71, 0xffff0000, v161
	v_pk_add_f32 v[68:69], v[62:63], v[74:75]
	v_pk_add_f32 v[62:63], v[60:61], v[72:73]
	v_cvt_pk_bf16_f32 v60, v64, v65
	v_lshl_add_u64 v[64:65], s[12:13], 0, v[222:223]
	v_pk_add_f32 v[66:67], v[66:67], v[70:71]
	v_lshl_add_u64 v[64:65], v[64:65], 0, v[214:215]
	v_cvt_pk_bf16_f32 v61, v66, v67
	v_cvt_pk_bf16_f32 v62, v62, v63
	v_cvt_pk_bf16_f32 v63, v68, v69
	global_store_dwordx4 v[64:65], v[60:63], off
	v_lshlrev_b32_e32 v66, 16, v158
	v_and_b32_e32 v67, 0xffff0000, v158
	v_lshlrev_b32_e32 v60, 16, v156
	v_and_b32_e32 v61, 0xffff0000, v156
	v_lshlrev_b32_e32 v62, 16, v157
	v_and_b32_e32 v63, 0xffff0000, v157
	v_lshlrev_b32_e32 v68, 16, v159
	v_and_b32_e32 v69, 0xffff0000, v159
	v_pk_add_f32 v[58:59], v[58:59], v[62:63]
	v_pk_add_f32 v[56:57], v[56:57], v[60:61]
	v_pk_add_f32 v[60:61], v[54:55], v[68:69]
	v_pk_add_f32 v[54:55], v[52:53], v[66:67]
	v_cvt_pk_bf16_f32 v52, v56, v57
	v_cvt_pk_bf16_f32 v53, v58, v59
	v_lshlrev_b32_e32 v56, 16, v154
	v_cvt_pk_bf16_f32 v54, v54, v55
	v_cvt_pk_bf16_f32 v55, v60, v61
	global_store_dwordx4 v[64:65], v[52:55], off offset:256
	v_and_b32_e32 v57, 0xffff0000, v154
	v_lshlrev_b32_e32 v58, 16, v155
	v_lshlrev_b32_e32 v52, 16, v152
	v_and_b32_e32 v53, 0xffff0000, v152
	v_and_b32_e32 v59, 0xffff0000, v155
; __device__ __forceinline__ unsigned cvt_pk_bf16(float lo, float hi) { unsigned r; asm volatile("v_cvt_pk_bf16_f32 %0, %1, %2" : "=v"(r) : "v"(lo), "v"(hi)); return r; }
; #define PG8_BAR __builtin_amdgcn_s_barrier()
;     __device__ __forceinline__ void operator()(const f32x4 (&acc)[2][2][4][2], const Unit& u, int wr, int wc, int fr, int fq) const {
;     ...
;                 for (int bj = 0; bj < 2; ++bj) xv[ai][m][bj] = *(const u32x4*)(XB + (size_t)(row0 + ai * HALF + m * 16) * ldc + col0 + bj * HALF);
; #pragma unroll
;         for (int ai = 0; ai < 2; ++ai) {
; #pragma unroll
;             for (int m = 0; m < 4; ++m) { const int row = row0 + ai * HALF + m * 16;
; #pragma unroll
;                 for (int bj = 0; bj < 2; ++bj) { f32x4 v0, v1; unpack8(xv[ai][m][bj], v0, v1); v0 = v0 + acc[ai][bj][m][0]; v1 = v1 + acc[ai][bj][m][1];
;                     u32x4 w; w.x = cvt_pk_bf16(v0[0], v0[1]); w.y = cvt_pk_bf16(v0[2], v0[3]); w.z = cvt_pk_bf16(v1[0], v1[1]); w.w = cvt_pk_bf16(v1[2], v1[3]);
;                     *(u32x4*)(XB + (size_t)row * ldc + col0 + bj * HALF) = w; } }
;             asm volatile("" ::: "memory"); }
; template <class Epi, class Sched, bool ALIGN_EPI = false, bool SP2 = false, bool I8 = false>
; __device__ __forceinline__ void gemm_phase(PG8_LAS unsigned char* lds, const Gemm g, const Sched& S, const Epi& E) {
;     ...
;         cur = nxt; cA = nA; cB = nB; ++ui;
;         if constexpr (ALIGN_EPI) { if (wr == 1) PG8_BAR; }
;     }
	v_pk_add_f32 v[48:49], v[48:49], v[52:53]
	v_lshlrev_b32_e32 v54, 16, v153
	v_and_b32_e32 v55, 0xffff0000, v153
	v_pk_add_f32 v[52:53], v[46:47], v[58:59]
	v_pk_add_f32 v[46:47], v[44:45], v[56:57]
	v_cvt_pk_bf16_f32 v44, v48, v49
	v_lshl_add_u64 v[48:49], s[12:13], 0, v[220:221]
	v_pk_add_f32 v[50:51], v[50:51], v[54:55]
	v_lshl_add_u64 v[48:49], v[48:49], 0, v[214:215]
	v_cvt_pk_bf16_f32 v45, v50, v51
	v_cvt_pk_bf16_f32 v46, v46, v47
	v_cvt_pk_bf16_f32 v47, v52, v53
	global_store_dwordx4 v[48:49], v[44:47], off
	v_lshlrev_b32_e32 v50, 16, v150
	v_and_b32_e32 v51, 0xffff0000, v150
	v_lshlrev_b32_e32 v44, 16, v148
	v_and_b32_e32 v45, 0xffff0000, v148
	v_lshlrev_b32_e32 v46, 16, v149
	v_and_b32_e32 v47, 0xffff0000, v149
	v_lshlrev_b32_e32 v52, 16, v151
	v_and_b32_e32 v53, 0xffff0000, v151
	v_pk_add_f32 v[42:43], v[42:43], v[46:47]
	v_pk_add_f32 v[40:41], v[40:41], v[44:45]
	v_pk_add_f32 v[44:45], v[38:39], v[52:53]
	v_pk_add_f32 v[38:39], v[36:37], v[50:51]
	v_cvt_pk_bf16_f32 v36, v40, v41
	v_cvt_pk_bf16_f32 v37, v42, v43
	v_lshlrev_b32_e32 v40, 16, v146
	v_cvt_pk_bf16_f32 v38, v38, v39
	v_cvt_pk_bf16_f32 v39, v44, v45
	global_store_dwordx4 v[48:49], v[36:39], off offset:256
	v_and_b32_e32 v41, 0xffff0000, v146
	v_lshlrev_b32_e32 v42, 16, v147
	v_lshlrev_b32_e32 v36, 16, v144
	v_and_b32_e32 v37, 0xffff0000, v144
	v_and_b32_e32 v43, 0xffff0000, v147
	v_pk_add_f32 v[32:33], v[32:33], v[36:37]
	v_lshlrev_b32_e32 v38, 16, v145
	v_and_b32_e32 v39, 0xffff0000, v145
	v_pk_add_f32 v[36:37], v[30:31], v[42:43]
	v_pk_add_f32 v[30:31], v[28:29], v[40:41]
	v_cvt_pk_bf16_f32 v28, v32, v33
	v_lshl_add_u64 v[32:33], s[12:13], 0, v[218:219]
	v_pk_add_f32 v[34:35], v[34:35], v[38:39]
	v_lshl_add_u64 v[32:33], v[32:33], 0, v[214:215]
	v_cvt_pk_bf16_f32 v29, v34, v35
	v_cvt_pk_bf16_f32 v30, v30, v31
	v_cvt_pk_bf16_f32 v31, v36, v37
	global_store_dwordx4 v[32:33], v[28:31], off
	v_lshlrev_b32_e32 v34, 16, v134
	v_and_b32_e32 v35, 0xffff0000, v134
	v_lshlrev_b32_e32 v28, 16, v132
	v_and_b32_e32 v29, 0xffff0000, v132
	v_lshlrev_b32_e32 v30, 16, v133
	v_and_b32_e32 v31, 0xffff0000, v133
	v_lshlrev_b32_e32 v36, 16, v135
	v_and_b32_e32 v37, 0xffff0000, v135
	v_pk_add_f32 v[26:27], v[26:27], v[30:31]
	v_pk_add_f32 v[24:25], v[24:25], v[28:29]
	v_pk_add_f32 v[28:29], v[22:23], v[36:37]
	v_pk_add_f32 v[22:23], v[20:21], v[34:35]
	v_cvt_pk_bf16_f32 v20, v24, v25
	v_cvt_pk_bf16_f32 v21, v26, v27
	v_lshlrev_b32_e32 v24, 16, v130
	v_cvt_pk_bf16_f32 v22, v22, v23
	v_cvt_pk_bf16_f32 v23, v28, v29
	global_store_dwordx4 v[32:33], v[20:23], off offset:256
	v_and_b32_e32 v25, 0xffff0000, v130
	v_lshlrev_b32_e32 v26, 16, v131
	v_lshlrev_b32_e32 v20, 16, v128
	v_and_b32_e32 v21, 0xffff0000, v128
	v_and_b32_e32 v27, 0xffff0000, v131
	v_pk_add_f32 v[16:17], v[16:17], v[20:21]
	v_lshlrev_b32_e32 v22, 16, v129
	v_and_b32_e32 v23, 0xffff0000, v129
	v_pk_add_f32 v[20:21], v[14:15], v[26:27]
	v_pk_add_f32 v[14:15], v[12:13], v[24:25]
	v_cvt_pk_bf16_f32 v12, v16, v17
	v_lshl_add_u64 v[16:17], s[12:13], 0, v[216:217]
	v_pk_add_f32 v[18:19], v[18:19], v[22:23]
	v_lshl_add_u64 v[16:17], v[16:17], 0, v[214:215]
	v_cvt_pk_bf16_f32 v13, v18, v19
	v_cvt_pk_bf16_f32 v14, v14, v15
	v_cvt_pk_bf16_f32 v15, v20, v21
	global_store_dwordx4 v[16:17], v[12:15], off
	v_lshlrev_b32_e32 v18, 16, v126
	v_and_b32_e32 v19, 0xffff0000, v126
	v_lshlrev_b32_e32 v12, 16, v124
	v_and_b32_e32 v13, 0xffff0000, v124
	v_lshlrev_b32_e32 v20, 16, v127
	v_and_b32_e32 v21, 0xffff0000, v127
	v_lshlrev_b32_e32 v14, 16, v125
	v_and_b32_e32 v15, 0xffff0000, v125
	v_pk_add_f32 v[8:9], v[8:9], v[12:13]
	v_pk_add_f32 v[12:13], v[6:7], v[20:21]
	v_pk_add_f32 v[6:7], v[4:5], v[18:19]
	v_pk_add_f32 v[10:11], v[10:11], v[14:15]
	v_cvt_pk_bf16_f32 v4, v8, v9
	s_nop 0
	v_cvt_pk_bf16_f32 v5, v10, v11
	v_cvt_pk_bf16_f32 v6, v6, v7
	v_cvt_pk_bf16_f32 v7, v12, v13
	global_store_dwordx4 v[16:17], v[4:7], off offset:256
	s_cbranch_vccnz .LBB0_1448
	s_andn2_b64 vcc, exec, s[10:11]
	s_cbranch_vccnz .LBB0_1447
	s_branch .LBB0_1447

; __device__ __forceinline__ unsigned xb_ld(unsigned* p)              { return __hip_atomic_load(p, __ATOMIC_RELAXED, __HIP_MEMORY_SCOPE_AGENT); }
; __device__ __forceinline__ void xcd_barrier_complete(unsigned* bar, unsigned x, unsigned& nloc, unsigned& nx) {
;     const unsigned G = gridDim.x * gridDim.y * gridDim.z;
;     unsigned sum, cnt, mine, sp = 0u;
;     for (;;) {
;         sum = 0u; cnt = 0u; mine = 0u;
; #pragma unroll
;         for (unsigned j = 0; j < 16; ++j) { const unsigned c = xb_ld(&bar[XB_XCNT(j)]); sum += c; cnt += (c > 0u) ? 1u : 0u; mine = (j == x) ? c : mine; }
; __device__ __forceinline__ void xcd_barrier(const XcdBarrier& b) {
;     asm volatile("s_waitcnt vmcnt(0)" ::: "memory");
;     __syncthreads();
;     if (threadIdx.x == 0) {
;         unsigned* bar = b.bar;
;         __builtin_amdgcn_s_waitcnt(0);
;         unsigned nloc = b.st[0], nx = b.st[1];
;         if (nloc == 0u) { xcd_barrier_complete(bar, b.x, nloc, nx); b.st[0] = nloc; b.st[1] = nx; }
.Lnoalign_2:
	s_barrier
.LBB0_1463:
	v_readlane_b32 s10, v254, 0
	v_readlane_b32 s11, v254, 1
	s_getreg_b32 s12, hwreg(HW_REG_XCC_ID, 0, 4)
	s_waitcnt vmcnt(0)
	s_barrier
	s_mov_b64 s[8:9], exec
	v_readlane_b32 s14, v254, 2
	v_readlane_b32 s15, v254, 3
	s_and_b64 s[14:15], s[8:9], s[14:15]
	s_mov_b64 exec, s[14:15]
	s_cbranch_execz .LBB0_1515
	v_readlane_b32 s13, v254, 39
	s_load_dwordx2 s[10:11], s[10:11], 0x98
	s_waitcnt vmcnt(0) expcnt(0) lgkmcnt(0)
	v_mov_b32_e32 v2, s13
	ds_read_b32 v5, v2
	v_readlane_b32 s13, v254, 40
	s_and_b32 s28, s12, 15
	s_waitcnt lgkmcnt(0)
	v_cmp_ne_u32_e32 vcc, 0, v5
	v_mov_b32_e32 v2, s13
	ds_read_b32 v4, v2
	s_cbranch_vccnz .LBB0_1479
	v_readlane_b32 s12, v254, 4
	v_readlane_b32 s13, v254, 5
	s_load_dwordx2 s[16:17], s[12:13], 0x4
	s_add_u32 s12, s10, 0x4200
	s_addc_u32 s13, s11, 0
	s_add_u32 s14, s10, 0x4400
	s_addc_u32 s15, s11, 0
	v_readlane_b32 s18, v254, 54
	s_waitcnt lgkmcnt(0)
	s_mul_i32 s39, s16, s18
	s_add_u32 s16, s10, 0x4500
	s_mul_i32 s39, s39, s17
	s_addc_u32 s17, s11, 0
	s_add_u32 s18, s10, 0x4600
	s_addc_u32 s19, s11, 0
	s_add_u32 s20, s10, 0x4700
	s_addc_u32 s21, s11, 0
	s_add_u32 s22, s10, 0x4800
	s_addc_u32 s23, s11, 0
	s_add_u32 s24, s10, 0x4900
	s_addc_u32 s25, s11, 0
	s_add_u32 s26, s10, 0x4a00
	s_addc_u32 s27, s11, 0
	s_add_u32 s36, s10, 0x4b00
	s_addc_u32 s37, s11, 0
	s_add_u32 s40, s10, 0x4c00
	s_addc_u32 s41, s11, 0
	s_add_u32 s44, s10, 0x4d00
	s_addc_u32 s45, s11, 0
	s_add_u32 s50, s10, 0x4e00
	s_addc_u32 s51, s11, 0
	s_add_u32 s54, s10, 0x4f00
	s_addc_u32 s55, s11, 0
	s_add_u32 s56, s10, 0x5000
	s_addc_u32 s57, s11, 0
	s_add_u32 s52, s10, 0x5100
	s_addc_u32 s53, s11, 0
	s_add_u32 s34, s10, 0x5200
	s_addc_u32 s35, s11, 0
	s_add_u32 s58, s10, 0x5300
	s_addc_u32 s59, s11, 0
	s_mov_b32 s42, 1
	s_branch .LBB0_1467

; __device__ __forceinline__ float fast_sigmoid(float x) { return __builtin_amdgcn_rcpf(1.0f + __expf(-x)); }
;     __device__ __forceinline__ void operator()(const i32x4 (&acc)[2][2][4][2], const Unit& u, int wr, int wc, int fr, int fq) const {
;         const int row0 = u.pm * BM + wr * 64 + fr, col0 = u.pn * HALF + wc * 32 + 8 * fq, brow = u.pn * BM + wc * 32 + 8 * fq;
;         const f32x4 dg0 = *(const f32x4*)(DB + brow), dg1 = *(const f32x4*)(DB + brow + 4), du0 = *(const f32x4*)(DB + brow + HALF), du1 = *(const f32x4*)(DB + brow + HALF + 4);
;         float rav[2][4];
; #pragma unroll
;         for (int ai = 0; ai < 2; ++ai)
; #pragma unroll
;             for (int m = 0; m < 4; ++m) rav[ai][m] = RA[row0 + ai * HALF + m * 16];
;         __builtin_amdgcn_sched_barrier(0);
; #pragma unroll
;         for (int ai = 0; ai < 2; ++ai)
; #pragma unroll
;             for (int m = 0; m < 4; ++m) { const int row = row0 + ai * HALF + m * 16; const float ra = rav[ai][m]; bf16_t* rowp = H + (size_t)row * ldh + col0;
;                 float hv[8];
; #pragma unroll
;                 for (int j = 0; j < 4; ++j) { const float g0 = (float)acc[ai][0][m][0][j] * ra * dg0[j], u0 = (float)acc[ai][1][m][0][j] * ra * du0[j]; hv[j] = g0 * fast_sigmoid(g0) * u0;
;                     const float g1 = (float)acc[ai][0][m][1][j] * ra * dg1[j], u1 = (float)acc[ai][1][m][1][j] * ra * du1[j]; hv[4 + j] = g1 * fast_sigmoid(g1) * u1; }
.Lkloop_exit_3:
.LBB0_1594:
	v_lshl_add_u32 v160, s35, 8, v159
	v_lshl_or_b32 v36, s34, 8, v169
	v_or_b32_e32 v178, 32, v160
	v_ashrrev_i32_e32 v37, 31, v36
	v_ashrrev_i32_e32 v161, 31, v160
	v_or_b32_e32 v182, 16, v160
	v_ashrrev_i32_e32 v179, 31, v178
	v_or_b32_e32 v174, 48, v160
	v_lshl_add_u64 v[144:145], v[36:37], 2, s[18:19]
	v_lshl_add_u64 v[162:163], v[160:161], 2, s[16:17]
	v_ashrrev_i32_e32 v183, 31, v182
	v_lshl_add_u64 v[172:173], v[178:179], 2, s[16:17]
	v_ashrrev_i32_e32 v175, 31, v174
	global_load_dwordx4 v[36:39], v[144:145], off offset:16
	global_load_dwordx4 v[44:47], v[144:145], off
	global_load_dwordx4 v[140:143], v[144:145], off offset:528
	s_nop 0
	global_load_dwordx4 v[144:147], v[144:145], off offset:512
	v_lshl_add_u64 v[164:165], v[182:183], 2, s[16:17]
	v_lshl_add_u64 v[184:185], v[174:175], 2, s[16:17]
	global_load_dword v188, v[162:163], off
	global_load_dword v180, v[164:165], off
	global_load_dword v176, v[172:173], off
	s_nop 0
	global_load_dword v172, v[184:185], off
	global_load_dword v170, v[162:163], off offset:512
	global_load_dword v168, v[162:163], off offset:576
	global_load_dword v166, v[162:163], off offset:640
	global_load_dword v158, v[162:163], off offset:704
	v_lshl_or_b32 v186, s34, 7, v169
	s_movk_i32 s23, 0x5600
	v_lshlrev_b32_e32 v186, 1, v186
	v_mad_u32_u24 v186, v160, s23, v186
	v_mov_b32_e32 v178, 0xbfb8aa3b
	v_mov_b32_e32 v179, 1.0
	v_cvt_f32_i32_e32 v136, v136
	v_cvt_f32_i32_e32 v137, v137
	v_cvt_f32_i32_e32 v138, v138
	v_cvt_f32_i32_e32 v139, v139
	v_cvt_f32_i32_e32 v132, v132
	v_cvt_f32_i32_e32 v133, v133
	v_cvt_f32_i32_e32 v134, v134
	v_cvt_f32_i32_e32 v135, v135
	v_cvt_f32_i32_e32 v128, v128
	v_cvt_f32_i32_e32 v129, v129
	v_cvt_f32_i32_e32 v130, v130
	v_cvt_f32_i32_e32 v131, v131
	v_cvt_f32_i32_e32 v124, v124
	v_cvt_f32_i32_e32 v125, v125
	v_cvt_f32_i32_e32 v126, v126
	v_cvt_f32_i32_e32 v127, v127
	v_cvt_f32_i32_e32 v120, v120
	v_cvt_f32_i32_e32 v121, v121
	v_cvt_f32_i32_e32 v122, v122
	v_cvt_f32_i32_e32 v123, v123
	v_cvt_f32_i32_e32 v116, v116
	v_cvt_f32_i32_e32 v117, v117
	v_cvt_f32_i32_e32 v118, v118
	v_cvt_f32_i32_e32 v119, v119
	v_cvt_f32_i32_e32 v112, v112
	v_cvt_f32_i32_e32 v113, v113
	v_cvt_f32_i32_e32 v114, v114
	v_cvt_f32_i32_e32 v115, v115
	v_cvt_f32_i32_e32 v108, v108
	v_cvt_f32_i32_e32 v109, v109
	v_cvt_f32_i32_e32 v110, v110
	v_cvt_f32_i32_e32 v111, v111
	v_cvt_f32_i32_e32 v104, v104
	v_cvt_f32_i32_e32 v105, v105
	v_cvt_f32_i32_e32 v106, v106
	v_cvt_f32_i32_e32 v107, v107
	v_cvt_f32_i32_e32 v100, v100
	v_cvt_f32_i32_e32 v101, v101
	v_cvt_f32_i32_e32 v102, v102
	v_cvt_f32_i32_e32 v103, v103
	v_cvt_f32_i32_e32 v96, v96
	v_cvt_f32_i32_e32 v97, v97
	v_cvt_f32_i32_e32 v98, v98
	v_cvt_f32_i32_e32 v99, v99
	v_cvt_f32_i32_e32 v92, v92
	v_cvt_f32_i32_e32 v93, v93
	v_cvt_f32_i32_e32 v94, v94
	v_cvt_f32_i32_e32 v95, v95
	v_cvt_f32_i32_e32 v88, v88
	v_cvt_f32_i32_e32 v89, v89
	v_cvt_f32_i32_e32 v90, v90
	v_cvt_f32_i32_e32 v91, v91
	v_cvt_f32_i32_e32 v84, v84
	v_cvt_f32_i32_e32 v85, v85
	v_cvt_f32_i32_e32 v86, v86
	v_cvt_f32_i32_e32 v87, v87
	v_cvt_f32_i32_e32 v80, v80
	v_cvt_f32_i32_e32 v81, v81
	v_cvt_f32_i32_e32 v82, v82
	v_cvt_f32_i32_e32 v83, v83
	v_cvt_f32_i32_e32 v76, v76
	v_cvt_f32_i32_e32 v77, v77
	v_cvt_f32_i32_e32 v78, v78
	v_cvt_f32_i32_e32 v79, v79
	v_cvt_f32_i32_e32 v72, v72
	v_cvt_f32_i32_e32 v73, v73
	v_cvt_f32_i32_e32 v74, v74
	v_cvt_f32_i32_e32 v75, v75
	v_cvt_f32_i32_e32 v68, v68
	v_cvt_f32_i32_e32 v69, v69
	v_cvt_f32_i32_e32 v70, v70
	v_cvt_f32_i32_e32 v71, v71
	v_cvt_f32_i32_e32 v64, v64
	v_cvt_f32_i32_e32 v65, v65
	v_cvt_f32_i32_e32 v66, v66
	v_cvt_f32_i32_e32 v67, v67
	v_cvt_f32_i32_e32 v60, v60
	v_cvt_f32_i32_e32 v61, v61
	v_cvt_f32_i32_e32 v62, v62
	v_cvt_f32_i32_e32 v63, v63
	v_cvt_f32_i32_e32 v56, v56
	v_cvt_f32_i32_e32 v57, v57
	v_cvt_f32_i32_e32 v58, v58
	v_cvt_f32_i32_e32 v59, v59
	v_cvt_f32_i32_e32 v52, v52
	v_cvt_f32_i32_e32 v53, v53
	v_cvt_f32_i32_e32 v54, v54
	v_cvt_f32_i32_e32 v55, v55
	v_cvt_f32_i32_e32 v48, v48
	v_cvt_f32_i32_e32 v49, v49
	v_cvt_f32_i32_e32 v50, v50
	v_cvt_f32_i32_e32 v51, v51
	v_cvt_f32_i32_e32 v40, v40
	v_cvt_f32_i32_e32 v41, v41
	v_cvt_f32_i32_e32 v42, v42
	v_cvt_f32_i32_e32 v43, v43
	v_cvt_f32_i32_e32 v32, v32
	v_cvt_f32_i32_e32 v33, v33
	v_cvt_f32_i32_e32 v34, v34
	v_cvt_f32_i32_e32 v35, v35
	v_cvt_f32_i32_e32 v28, v28
	v_cvt_f32_i32_e32 v29, v29
	v_cvt_f32_i32_e32 v30, v30
	v_cvt_f32_i32_e32 v31, v31
	v_cvt_f32_i32_e32 v24, v24
	v_cvt_f32_i32_e32 v25, v25
	v_cvt_f32_i32_e32 v26, v26
	v_cvt_f32_i32_e32 v27, v27
	v_cvt_f32_i32_e32 v20, v20
	v_cvt_f32_i32_e32 v21, v21
	v_cvt_f32_i32_e32 v22, v22
	v_cvt_f32_i32_e32 v23, v23
	v_cvt_f32_i32_e32 v16, v16
	v_cvt_f32_i32_e32 v17, v17
	v_cvt_f32_i32_e32 v18, v18
	v_cvt_f32_i32_e32 v19, v19
	v_cvt_f32_i32_e32 v12, v12
	v_cvt_f32_i32_e32 v13, v13
	v_cvt_f32_i32_e32 v14, v14
	v_cvt_f32_i32_e32 v15, v15
	v_cvt_f32_i32_e32 v8, v8
	v_cvt_f32_i32_e32 v9, v9
	v_cvt_f32_i32_e32 v10, v10
	v_cvt_f32_i32_e32 v11, v11
	v_cvt_f32_i32_e32 v4, v4
	v_cvt_f32_i32_e32 v5, v5
	v_cvt_f32_i32_e32 v6, v6
	v_cvt_f32_i32_e32 v7, v7
	s_waitcnt vmcnt(0)
; __device__ __forceinline__ unsigned cvt_pk_bf16(float lo, float hi) { unsigned r; asm volatile("v_cvt_pk_bf16_f32 %0, %1, %2" : "=v"(r) : "v"(lo), "v"(hi)); return r; }
; __device__ __forceinline__ float fast_sigmoid(float x) { return __builtin_amdgcn_rcpf(1.0f + __expf(-x)); }
;     __device__ __forceinline__ void operator()(const i32x4 (&acc)[2][2][4][2], const Unit& u, int wr, int wc, int fr, int fq) const {
;     ...
; #pragma unroll
;         for (int ai = 0; ai < 2; ++ai)
; #pragma unroll
;             for (int m = 0; m < 4; ++m) { const int row = row0 + ai * HALF + m * 16; const float ra = rav[ai][m]; bf16_t* rowp = H + (size_t)row * ldh + col0;
;                 float hv[8];
; #pragma unroll
;                 for (int j = 0; j < 4; ++j) { const float g0 = (float)acc[ai][0][m][0][j] * ra * dg0[j], u0 = (float)acc[ai][1][m][0][j] * ra * du0[j]; hv[j] = g0 * fast_sigmoid(g0) * u0;
;                     const float g1 = (float)acc[ai][0][m][1][j] * ra * dg1[j], u1 = (float)acc[ai][1][m][1][j] * ra * du1[j]; hv[4 + j] = g1 * fast_sigmoid(g1) * u1; }
;                 u32x4 w; w.x = cvt_pk_bf16(hv[0], hv[1]); w.y = cvt_pk_bf16(hv[2], hv[3]); w.z = cvt_pk_bf16(hv[4], hv[5]); w.w = cvt_pk_bf16(hv[6], hv[7]);
;                 *(u32x4*)rowp = w; }
	v_pk_mul_f32 v[136:137], v[188:189], v[136:137] op_sel_hi:[0,1]
	v_pk_mul_f32 v[132:133], v[188:189], v[132:133] op_sel_hi:[0,1]
	v_pk_mul_f32 v[138:139], v[188:189], v[138:139] op_sel_hi:[0,1]
	v_pk_mul_f32 v[134:135], v[188:189], v[134:135] op_sel_hi:[0,1]
	v_pk_mul_f32 v[128:129], v[188:189], v[128:129] op_sel_hi:[0,1]
	v_pk_mul_f32 v[124:125], v[188:189], v[124:125] op_sel_hi:[0,1]
	v_pk_mul_f32 v[130:131], v[188:189], v[130:131] op_sel_hi:[0,1]
	v_pk_mul_f32 v[126:127], v[188:189], v[126:127] op_sel_hi:[0,1]
	v_pk_mul_f32 v[136:137], v[44:45], v[136:137]
	v_pk_mul_f32 v[132:133], v[144:145], v[132:133]
	v_pk_mul_f32 v[138:139], v[46:47], v[138:139]
	v_pk_mul_f32 v[134:135], v[146:147], v[134:135]
	v_pk_mul_f32 v[128:129], v[36:37], v[128:129]
	v_pk_mul_f32 v[124:125], v[140:141], v[124:125]
	v_pk_mul_f32 v[130:131], v[38:39], v[130:131]
	v_pk_mul_f32 v[126:127], v[142:143], v[126:127]
	v_pk_mul_f32 v[160:161], v[178:179], v[136:137] op_sel_hi:[0,1]
	v_pk_mul_f32 v[162:163], v[178:179], v[138:139] op_sel_hi:[0,1]
	v_exp_f32_e32 v160, v160
	v_exp_f32_e32 v161, v161
	v_exp_f32_e32 v162, v162
	v_exp_f32_e32 v163, v163
	v_pk_add_f32 v[160:161], v[178:179], v[160:161] op_sel:[1,0] op_sel_hi:[1,1]
	v_pk_add_f32 v[162:163], v[178:179], v[162:163] op_sel:[1,0] op_sel_hi:[1,1]
	v_rcp_f32_e32 v160, v160
	v_rcp_f32_e32 v161, v161
	v_rcp_f32_e32 v162, v162
	v_rcp_f32_e32 v163, v163
	v_pk_mul_f32 v[136:137], v[136:137], v[160:161]
	v_pk_mul_f32 v[138:139], v[138:139], v[162:163]
	v_pk_mul_f32 v[136:137], v[132:133], v[136:137]
	v_pk_mul_f32 v[138:139], v[134:135], v[138:139]
	v_pk_mul_f32 v[160:161], v[178:179], v[128:129] op_sel_hi:[0,1]
	v_pk_mul_f32 v[162:163], v[178:179], v[130:131] op_sel_hi:[0,1]
	v_exp_f32_e32 v160, v160
	v_exp_f32_e32 v161, v161
	v_exp_f32_e32 v162, v162
	v_exp_f32_e32 v163, v163
	v_pk_add_f32 v[160:161], v[178:179], v[160:161] op_sel:[1,0] op_sel_hi:[1,1]
	v_pk_add_f32 v[162:163], v[178:179], v[162:163] op_sel:[1,0] op_sel_hi:[1,1]
	v_rcp_f32_e32 v160, v160
	v_rcp_f32_e32 v161, v161
	v_rcp_f32_e32 v162, v162
	v_rcp_f32_e32 v163, v163
	v_pk_mul_f32 v[128:129], v[128:129], v[160:161]
	v_pk_mul_f32 v[130:131], v[130:131], v[162:163]
	v_pk_mul_f32 v[128:129], v[124:125], v[128:129]
	v_pk_mul_f32 v[130:131], v[126:127], v[130:131]
	v_cvt_pk_bf16_f32 v136, v136, v137
	v_cvt_pk_bf16_f32 v137, v138, v139
	v_cvt_pk_bf16_f32 v138, v128, v129
	v_cvt_pk_bf16_f32 v139, v130, v131
	global_store_dwordx4 v186, v[136:139], s[14:15]
	v_pk_mul_f32 v[120:121], v[180:181], v[120:121] op_sel_hi:[0,1]
	v_pk_mul_f32 v[116:117], v[180:181], v[116:117] op_sel_hi:[0,1]
	v_pk_mul_f32 v[122:123], v[180:181], v[122:123] op_sel_hi:[0,1]
	v_pk_mul_f32 v[118:119], v[180:181], v[118:119] op_sel_hi:[0,1]
	v_pk_mul_f32 v[112:113], v[180:181], v[112:113] op_sel_hi:[0,1]
	v_pk_mul_f32 v[108:109], v[180:181], v[108:109] op_sel_hi:[0,1]
	v_pk_mul_f32 v[114:115], v[180:181], v[114:115] op_sel_hi:[0,1]
	v_pk_mul_f32 v[110:111], v[180:181], v[110:111] op_sel_hi:[0,1]
	v_pk_mul_f32 v[120:121], v[44:45], v[120:121]
	v_pk_mul_f32 v[116:117], v[144:145], v[116:117]
	v_pk_mul_f32 v[122:123], v[46:47], v[122:123]
	v_pk_mul_f32 v[118:119], v[146:147], v[118:119]
	v_pk_mul_f32 v[112:113], v[36:37], v[112:113]
	v_pk_mul_f32 v[108:109], v[140:141], v[108:109]
	v_pk_mul_f32 v[114:115], v[38:39], v[114:115]
	v_pk_mul_f32 v[110:111], v[142:143], v[110:111]
	v_pk_mul_f32 v[160:161], v[178:179], v[120:121] op_sel_hi:[0,1]
	v_pk_mul_f32 v[162:163], v[178:179], v[122:123] op_sel_hi:[0,1]
	v_exp_f32_e32 v160, v160
	v_exp_f32_e32 v161, v161
	v_exp_f32_e32 v162, v162
	v_exp_f32_e32 v163, v163
	v_pk_add_f32 v[160:161], v[178:179], v[160:161] op_sel:[1,0] op_sel_hi:[1,1]
	v_pk_add_f32 v[162:163], v[178:179], v[162:163] op_sel:[1,0] op_sel_hi:[1,1]
	v_rcp_f32_e32 v160, v160
	v_rcp_f32_e32 v161, v161
	v_rcp_f32_e32 v162, v162
	v_rcp_f32_e32 v163, v163
	v_pk_mul_f32 v[120:121], v[120:121], v[160:161]
	v_pk_mul_f32 v[122:123], v[122:123], v[162:163]
	v_pk_mul_f32 v[120:121], v[116:117], v[120:121]
	v_pk_mul_f32 v[122:123], v[118:119], v[122:123]
	v_pk_mul_f32 v[160:161], v[178:179], v[112:113] op_sel_hi:[0,1]
	v_pk_mul_f32 v[162:163], v[178:179], v[114:115] op_sel_hi:[0,1]
	v_exp_f32_e32 v160, v160
	v_exp_f32_e32 v161, v161
	v_exp_f32_e32 v162, v162
	v_exp_f32_e32 v163, v163
	v_pk_add_f32 v[160:161], v[178:179], v[160:161] op_sel:[1,0] op_sel_hi:[1,1]
	v_pk_add_f32 v[162:163], v[178:179], v[162:163] op_sel:[1,0] op_sel_hi:[1,1]
	v_rcp_f32_e32 v160, v160
	v_rcp_f32_e32 v161, v161
	v_rcp_f32_e32 v162, v162
	v_rcp_f32_e32 v163, v163
	v_pk_mul_f32 v[112:113], v[112:113], v[160:161]
	v_pk_mul_f32 v[114:115], v[114:115], v[162:163]
	v_pk_mul_f32 v[112:113], v[108:109], v[112:113]
	v_pk_mul_f32 v[114:115], v[110:111], v[114:115]
	v_cvt_pk_bf16_f32 v120, v120, v121
	v_cvt_pk_bf16_f32 v121, v122, v123
	v_cvt_pk_bf16_f32 v122, v112, v113
	v_cvt_pk_bf16_f32 v123, v114, v115
	v_add_u32_e32 v187, 0x56000, v186
	global_store_dwordx4 v187, v[120:123], s[14:15]
	v_pk_mul_f32 v[104:105], v[176:177], v[104:105] op_sel_hi:[0,1]
	v_pk_mul_f32 v[100:101], v[176:177], v[100:101] op_sel_hi:[0,1]
	v_pk_mul_f32 v[106:107], v[176:177], v[106:107] op_sel_hi:[0,1]
	v_pk_mul_f32 v[102:103], v[176:177], v[102:103] op_sel_hi:[0,1]
	v_pk_mul_f32 v[96:97], v[176:177], v[96:97] op_sel_hi:[0,1]
	v_pk_mul_f32 v[92:93], v[176:177], v[92:93] op_sel_hi:[0,1]
	v_pk_mul_f32 v[98:99], v[176:177], v[98:99] op_sel_hi:[0,1]
	v_pk_mul_f32 v[94:95], v[176:177], v[94:95] op_sel_hi:[0,1]
	v_pk_mul_f32 v[104:105], v[44:45], v[104:105]
	v_pk_mul_f32 v[100:101], v[144:145], v[100:101]
	v_pk_mul_f32 v[106:107], v[46:47], v[106:107]
; __device__ __forceinline__ unsigned cvt_pk_bf16(float lo, float hi) { unsigned r; asm volatile("v_cvt_pk_bf16_f32 %0, %1, %2" : "=v"(r) : "v"(lo), "v"(hi)); return r; }
; __device__ __forceinline__ float fast_sigmoid(float x) { return __builtin_amdgcn_rcpf(1.0f + __expf(-x)); }
;     __device__ __forceinline__ void operator()(const i32x4 (&acc)[2][2][4][2], const Unit& u, int wr, int wc, int fr, int fq) const {
;     ...
; #pragma unroll
;         for (int ai = 0; ai < 2; ++ai)
; #pragma unroll
;             for (int m = 0; m < 4; ++m) { const int row = row0 + ai * HALF + m * 16; const float ra = rav[ai][m]; bf16_t* rowp = H + (size_t)row * ldh + col0;
;                 float hv[8];
; #pragma unroll
;                 for (int j = 0; j < 4; ++j) { const float g0 = (float)acc[ai][0][m][0][j] * ra * dg0[j], u0 = (float)acc[ai][1][m][0][j] * ra * du0[j]; hv[j] = g0 * fast_sigmoid(g0) * u0;
;                     const float g1 = (float)acc[ai][0][m][1][j] * ra * dg1[j], u1 = (float)acc[ai][1][m][1][j] * ra * du1[j]; hv[4 + j] = g1 * fast_sigmoid(g1) * u1; }
;                 u32x4 w; w.x = cvt_pk_bf16(hv[0], hv[1]); w.y = cvt_pk_bf16(hv[2], hv[3]); w.z = cvt_pk_bf16(hv[4], hv[5]); w.w = cvt_pk_bf16(hv[6], hv[7]);
;                 *(u32x4*)rowp = w; }
	v_pk_mul_f32 v[102:103], v[146:147], v[102:103]
	v_pk_mul_f32 v[96:97], v[36:37], v[96:97]
	v_pk_mul_f32 v[92:93], v[140:141], v[92:93]
	v_pk_mul_f32 v[98:99], v[38:39], v[98:99]
	v_pk_mul_f32 v[94:95], v[142:143], v[94:95]
	v_pk_mul_f32 v[160:161], v[178:179], v[104:105] op_sel_hi:[0,1]
	v_pk_mul_f32 v[162:163], v[178:179], v[106:107] op_sel_hi:[0,1]
	v_exp_f32_e32 v160, v160
	v_exp_f32_e32 v161, v161
	v_exp_f32_e32 v162, v162
	v_exp_f32_e32 v163, v163
	v_pk_add_f32 v[160:161], v[178:179], v[160:161] op_sel:[1,0] op_sel_hi:[1,1]
	v_pk_add_f32 v[162:163], v[178:179], v[162:163] op_sel:[1,0] op_sel_hi:[1,1]
	v_rcp_f32_e32 v160, v160
	v_rcp_f32_e32 v161, v161
	v_rcp_f32_e32 v162, v162
	v_rcp_f32_e32 v163, v163
	v_pk_mul_f32 v[104:105], v[104:105], v[160:161]
	v_pk_mul_f32 v[106:107], v[106:107], v[162:163]
	v_pk_mul_f32 v[104:105], v[100:101], v[104:105]
	v_pk_mul_f32 v[106:107], v[102:103], v[106:107]
	v_pk_mul_f32 v[160:161], v[178:179], v[96:97] op_sel_hi:[0,1]
	v_pk_mul_f32 v[162:163], v[178:179], v[98:99] op_sel_hi:[0,1]
	v_exp_f32_e32 v160, v160
	v_exp_f32_e32 v161, v161
	v_exp_f32_e32 v162, v162
	v_exp_f32_e32 v163, v163
	v_pk_add_f32 v[160:161], v[178:179], v[160:161] op_sel:[1,0] op_sel_hi:[1,1]
	v_pk_add_f32 v[162:163], v[178:179], v[162:163] op_sel:[1,0] op_sel_hi:[1,1]
	v_rcp_f32_e32 v160, v160
	v_rcp_f32_e32 v161, v161
	v_rcp_f32_e32 v162, v162
	v_rcp_f32_e32 v163, v163
	v_pk_mul_f32 v[96:97], v[96:97], v[160:161]
	v_pk_mul_f32 v[98:99], v[98:99], v[162:163]
	v_pk_mul_f32 v[96:97], v[92:93], v[96:97]
	v_pk_mul_f32 v[98:99], v[94:95], v[98:99]
	v_cvt_pk_bf16_f32 v104, v104, v105
	v_cvt_pk_bf16_f32 v105, v106, v107
	v_cvt_pk_bf16_f32 v106, v96, v97
	v_cvt_pk_bf16_f32 v107, v98, v99
	v_add_u32_e32 v187, 0xac000, v186
	global_store_dwordx4 v187, v[104:107], s[14:15]
	v_pk_mul_f32 v[88:89], v[172:173], v[88:89] op_sel_hi:[0,1]
	v_pk_mul_f32 v[84:85], v[172:173], v[84:85] op_sel_hi:[0,1]
	v_pk_mul_f32 v[90:91], v[172:173], v[90:91] op_sel_hi:[0,1]
	v_pk_mul_f32 v[86:87], v[172:173], v[86:87] op_sel_hi:[0,1]
	v_pk_mul_f32 v[80:81], v[172:173], v[80:81] op_sel_hi:[0,1]
	v_pk_mul_f32 v[76:77], v[172:173], v[76:77] op_sel_hi:[0,1]
	v_pk_mul_f32 v[82:83], v[172:173], v[82:83] op_sel_hi:[0,1]
	v_pk_mul_f32 v[78:79], v[172:173], v[78:79] op_sel_hi:[0,1]
	v_pk_mul_f32 v[88:89], v[44:45], v[88:89]
	v_pk_mul_f32 v[84:85], v[144:145], v[84:85]
	v_pk_mul_f32 v[90:91], v[46:47], v[90:91]
	v_pk_mul_f32 v[86:87], v[146:147], v[86:87]
	v_pk_mul_f32 v[80:81], v[36:37], v[80:81]
	v_pk_mul_f32 v[76:77], v[140:141], v[76:77]
	v_pk_mul_f32 v[82:83], v[38:39], v[82:83]
	v_pk_mul_f32 v[78:79], v[142:143], v[78:79]
	v_pk_mul_f32 v[160:161], v[178:179], v[88:89] op_sel_hi:[0,1]
	v_pk_mul_f32 v[162:163], v[178:179], v[90:91] op_sel_hi:[0,1]
	v_exp_f32_e32 v160, v160
	v_exp_f32_e32 v161, v161
	v_exp_f32_e32 v162, v162
	v_exp_f32_e32 v163, v163
	v_pk_add_f32 v[160:161], v[178:179], v[160:161] op_sel:[1,0] op_sel_hi:[1,1]
	v_pk_add_f32 v[162:163], v[178:179], v[162:163] op_sel:[1,0] op_sel_hi:[1,1]
	v_rcp_f32_e32 v160, v160
	v_rcp_f32_e32 v161, v161
	v_rcp_f32_e32 v162, v162
	v_rcp_f32_e32 v163, v163
	v_pk_mul_f32 v[88:89], v[88:89], v[160:161]
	v_pk_mul_f32 v[90:91], v[90:91], v[162:163]
	v_pk_mul_f32 v[88:89], v[84:85], v[88:89]
	v_pk_mul_f32 v[90:91], v[86:87], v[90:91]
	v_pk_mul_f32 v[160:161], v[178:179], v[80:81] op_sel_hi:[0,1]
	v_pk_mul_f32 v[162:163], v[178:179], v[82:83] op_sel_hi:[0,1]
	v_exp_f32_e32 v160, v160
	v_exp_f32_e32 v161, v161
	v_exp_f32_e32 v162, v162
	v_exp_f32_e32 v163, v163
	v_pk_add_f32 v[160:161], v[178:179], v[160:161] op_sel:[1,0] op_sel_hi:[1,1]
	v_pk_add_f32 v[162:163], v[178:179], v[162:163] op_sel:[1,0] op_sel_hi:[1,1]
	v_rcp_f32_e32 v160, v160
	v_rcp_f32_e32 v161, v161
	v_rcp_f32_e32 v162, v162
	v_rcp_f32_e32 v163, v163
	v_pk_mul_f32 v[80:81], v[80:81], v[160:161]
	v_pk_mul_f32 v[82:83], v[82:83], v[162:163]
	v_pk_mul_f32 v[80:81], v[76:77], v[80:81]
	v_pk_mul_f32 v[82:83], v[78:79], v[82:83]
	v_cvt_pk_bf16_f32 v88, v88, v89
	v_cvt_pk_bf16_f32 v89, v90, v91
	v_cvt_pk_bf16_f32 v90, v80, v81
	v_cvt_pk_bf16_f32 v91, v82, v83
	v_add_u32_e32 v187, 0x102000, v186
	global_store_dwordx4 v187, v[88:91], s[14:15]
	v_pk_mul_f32 v[72:73], v[170:171], v[72:73] op_sel_hi:[0,1]
	v_pk_mul_f32 v[68:69], v[170:171], v[68:69] op_sel_hi:[0,1]
	v_pk_mul_f32 v[74:75], v[170:171], v[74:75] op_sel_hi:[0,1]
	v_pk_mul_f32 v[70:71], v[170:171], v[70:71] op_sel_hi:[0,1]
	v_pk_mul_f32 v[64:65], v[170:171], v[64:65] op_sel_hi:[0,1]
	v_pk_mul_f32 v[60:61], v[170:171], v[60:61] op_sel_hi:[0,1]
	v_pk_mul_f32 v[66:67], v[170:171], v[66:67] op_sel_hi:[0,1]
	v_pk_mul_f32 v[62:63], v[170:171], v[62:63] op_sel_hi:[0,1]
	v_pk_mul_f32 v[72:73], v[44:45], v[72:73]
	v_pk_mul_f32 v[68:69], v[144:145], v[68:69]
	v_pk_mul_f32 v[74:75], v[46:47], v[74:75]
	v_pk_mul_f32 v[70:71], v[146:147], v[70:71]
	v_pk_mul_f32 v[64:65], v[36:37], v[64:65]
	v_pk_mul_f32 v[60:61], v[140:141], v[60:61]
	v_pk_mul_f32 v[66:67], v[38:39], v[66:67]
	v_pk_mul_f32 v[62:63], v[142:143], v[62:63]
	v_pk_mul_f32 v[160:161], v[178:179], v[72:73] op_sel_hi:[0,1]
	v_pk_mul_f32 v[162:163], v[178:179], v[74:75] op_sel_hi:[0,1]
	v_exp_f32_e32 v160, v160
	v_exp_f32_e32 v161, v161
	v_exp_f32_e32 v162, v162
	v_exp_f32_e32 v163, v163
	v_pk_add_f32 v[160:161], v[178:179], v[160:161] op_sel:[1,0] op_sel_hi:[1,1]
	v_pk_add_f32 v[162:163], v[178:179], v[162:163] op_sel:[1,0] op_sel_hi:[1,1]
	v_rcp_f32_e32 v160, v160
	v_rcp_f32_e32 v161, v161
	v_rcp_f32_e32 v162, v162
	v_rcp_f32_e32 v163, v163
	v_pk_mul_f32 v[72:73], v[72:73], v[160:161]
	v_pk_mul_f32 v[74:75], v[74:75], v[162:163]
	v_pk_mul_f32 v[72:73], v[68:69], v[72:73]
; __device__ __forceinline__ unsigned cvt_pk_bf16(float lo, float hi) { unsigned r; asm volatile("v_cvt_pk_bf16_f32 %0, %1, %2" : "=v"(r) : "v"(lo), "v"(hi)); return r; }
; __device__ __forceinline__ float fast_sigmoid(float x) { return __builtin_amdgcn_rcpf(1.0f + __expf(-x)); }
;     __device__ __forceinline__ void operator()(const i32x4 (&acc)[2][2][4][2], const Unit& u, int wr, int wc, int fr, int fq) const {
;     ...
; #pragma unroll
;         for (int ai = 0; ai < 2; ++ai)
; #pragma unroll
;             for (int m = 0; m < 4; ++m) { const int row = row0 + ai * HALF + m * 16; const float ra = rav[ai][m]; bf16_t* rowp = H + (size_t)row * ldh + col0;
;                 float hv[8];
; #pragma unroll
;                 for (int j = 0; j < 4; ++j) { const float g0 = (float)acc[ai][0][m][0][j] * ra * dg0[j], u0 = (float)acc[ai][1][m][0][j] * ra * du0[j]; hv[j] = g0 * fast_sigmoid(g0) * u0;
;                     const float g1 = (float)acc[ai][0][m][1][j] * ra * dg1[j], u1 = (float)acc[ai][1][m][1][j] * ra * du1[j]; hv[4 + j] = g1 * fast_sigmoid(g1) * u1; }
;                 u32x4 w; w.x = cvt_pk_bf16(hv[0], hv[1]); w.y = cvt_pk_bf16(hv[2], hv[3]); w.z = cvt_pk_bf16(hv[4], hv[5]); w.w = cvt_pk_bf16(hv[6], hv[7]);
;                 *(u32x4*)rowp = w; }
	v_pk_mul_f32 v[74:75], v[70:71], v[74:75]
	v_pk_mul_f32 v[160:161], v[178:179], v[64:65] op_sel_hi:[0,1]
	v_pk_mul_f32 v[162:163], v[178:179], v[66:67] op_sel_hi:[0,1]
	v_exp_f32_e32 v160, v160
	v_exp_f32_e32 v161, v161
	v_exp_f32_e32 v162, v162
	v_exp_f32_e32 v163, v163
	v_pk_add_f32 v[160:161], v[178:179], v[160:161] op_sel:[1,0] op_sel_hi:[1,1]
	v_pk_add_f32 v[162:163], v[178:179], v[162:163] op_sel:[1,0] op_sel_hi:[1,1]
	v_rcp_f32_e32 v160, v160
	v_rcp_f32_e32 v161, v161
	v_rcp_f32_e32 v162, v162
	v_rcp_f32_e32 v163, v163
	v_pk_mul_f32 v[64:65], v[64:65], v[160:161]
	v_pk_mul_f32 v[66:67], v[66:67], v[162:163]
	v_pk_mul_f32 v[64:65], v[60:61], v[64:65]
	v_pk_mul_f32 v[66:67], v[62:63], v[66:67]
	v_cvt_pk_bf16_f32 v72, v72, v73
	v_cvt_pk_bf16_f32 v73, v74, v75
	v_cvt_pk_bf16_f32 v74, v64, v65
	v_cvt_pk_bf16_f32 v75, v66, v67
	v_add_u32_e32 v187, 0x2b0000, v186
	global_store_dwordx4 v187, v[72:75], s[14:15]
	v_pk_mul_f32 v[56:57], v[168:169], v[56:57] op_sel_hi:[0,1]
	v_pk_mul_f32 v[52:53], v[168:169], v[52:53] op_sel_hi:[0,1]
	v_pk_mul_f32 v[58:59], v[168:169], v[58:59] op_sel_hi:[0,1]
	v_pk_mul_f32 v[54:55], v[168:169], v[54:55] op_sel_hi:[0,1]
	v_pk_mul_f32 v[48:49], v[168:169], v[48:49] op_sel_hi:[0,1]
	v_pk_mul_f32 v[40:41], v[168:169], v[40:41] op_sel_hi:[0,1]
	v_pk_mul_f32 v[50:51], v[168:169], v[50:51] op_sel_hi:[0,1]
	v_pk_mul_f32 v[42:43], v[168:169], v[42:43] op_sel_hi:[0,1]
	v_pk_mul_f32 v[56:57], v[44:45], v[56:57]
	v_pk_mul_f32 v[52:53], v[144:145], v[52:53]
	v_pk_mul_f32 v[58:59], v[46:47], v[58:59]
	v_pk_mul_f32 v[54:55], v[146:147], v[54:55]
	v_pk_mul_f32 v[48:49], v[36:37], v[48:49]
	v_pk_mul_f32 v[40:41], v[140:141], v[40:41]
	v_pk_mul_f32 v[50:51], v[38:39], v[50:51]
	v_pk_mul_f32 v[42:43], v[142:143], v[42:43]
	v_pk_mul_f32 v[160:161], v[178:179], v[56:57] op_sel_hi:[0,1]
	v_pk_mul_f32 v[162:163], v[178:179], v[58:59] op_sel_hi:[0,1]
	v_exp_f32_e32 v160, v160
	v_exp_f32_e32 v161, v161
	v_exp_f32_e32 v162, v162
	v_exp_f32_e32 v163, v163
	v_pk_add_f32 v[160:161], v[178:179], v[160:161] op_sel:[1,0] op_sel_hi:[1,1]
	v_pk_add_f32 v[162:163], v[178:179], v[162:163] op_sel:[1,0] op_sel_hi:[1,1]
	v_rcp_f32_e32 v160, v160
	v_rcp_f32_e32 v161, v161
	v_rcp_f32_e32 v162, v162
	v_rcp_f32_e32 v163, v163
	v_pk_mul_f32 v[56:57], v[56:57], v[160:161]
	v_pk_mul_f32 v[58:59], v[58:59], v[162:163]
	v_pk_mul_f32 v[56:57], v[52:53], v[56:57]
	v_pk_mul_f32 v[58:59], v[54:55], v[58:59]
	v_pk_mul_f32 v[160:161], v[178:179], v[48:49] op_sel_hi:[0,1]
	v_pk_mul_f32 v[162:163], v[178:179], v[50:51] op_sel_hi:[0,1]
	v_exp_f32_e32 v160, v160
	v_exp_f32_e32 v161, v161
	v_exp_f32_e32 v162, v162
	v_exp_f32_e32 v163, v163
	v_pk_add_f32 v[160:161], v[178:179], v[160:161] op_sel:[1,0] op_sel_hi:[1,1]
	v_pk_add_f32 v[162:163], v[178:179], v[162:163] op_sel:[1,0] op_sel_hi:[1,1]
	v_rcp_f32_e32 v160, v160
	v_rcp_f32_e32 v161, v161
	v_rcp_f32_e32 v162, v162
	v_rcp_f32_e32 v163, v163
	v_pk_mul_f32 v[48:49], v[48:49], v[160:161]
	v_pk_mul_f32 v[50:51], v[50:51], v[162:163]
	v_pk_mul_f32 v[48:49], v[40:41], v[48:49]
	v_pk_mul_f32 v[50:51], v[42:43], v[50:51]
	v_cvt_pk_bf16_f32 v56, v56, v57
	v_cvt_pk_bf16_f32 v57, v58, v59
	v_cvt_pk_bf16_f32 v58, v48, v49
	v_cvt_pk_bf16_f32 v59, v50, v51
	v_add_u32_e32 v187, 0x306000, v186
	global_store_dwordx4 v187, v[56:59], s[14:15]
	v_pk_mul_f32 v[32:33], v[166:167], v[32:33] op_sel_hi:[0,1]
	v_pk_mul_f32 v[28:29], v[166:167], v[28:29] op_sel_hi:[0,1]
	v_pk_mul_f32 v[34:35], v[166:167], v[34:35] op_sel_hi:[0,1]
	v_pk_mul_f32 v[30:31], v[166:167], v[30:31] op_sel_hi:[0,1]
	v_pk_mul_f32 v[24:25], v[166:167], v[24:25] op_sel_hi:[0,1]
	v_pk_mul_f32 v[20:21], v[166:167], v[20:21] op_sel_hi:[0,1]
	v_pk_mul_f32 v[26:27], v[166:167], v[26:27] op_sel_hi:[0,1]
	v_pk_mul_f32 v[22:23], v[166:167], v[22:23] op_sel_hi:[0,1]
	v_pk_mul_f32 v[32:33], v[44:45], v[32:33]
	v_pk_mul_f32 v[28:29], v[144:145], v[28:29]
	v_pk_mul_f32 v[34:35], v[46:47], v[34:35]
	v_pk_mul_f32 v[30:31], v[146:147], v[30:31]
	v_pk_mul_f32 v[24:25], v[36:37], v[24:25]
	v_pk_mul_f32 v[20:21], v[140:141], v[20:21]
	v_pk_mul_f32 v[26:27], v[38:39], v[26:27]
	v_pk_mul_f32 v[22:23], v[142:143], v[22:23]
	v_pk_mul_f32 v[160:161], v[178:179], v[32:33] op_sel_hi:[0,1]
	v_pk_mul_f32 v[162:163], v[178:179], v[34:35] op_sel_hi:[0,1]
	v_exp_f32_e32 v160, v160
	v_exp_f32_e32 v161, v161
	v_exp_f32_e32 v162, v162
	v_exp_f32_e32 v163, v163
	v_pk_add_f32 v[160:161], v[178:179], v[160:161] op_sel:[1,0] op_sel_hi:[1,1]
	v_pk_add_f32 v[162:163], v[178:179], v[162:163] op_sel:[1,0] op_sel_hi:[1,1]
	v_rcp_f32_e32 v160, v160
	v_rcp_f32_e32 v161, v161
	v_rcp_f32_e32 v162, v162
	v_rcp_f32_e32 v163, v163
	v_pk_mul_f32 v[32:33], v[32:33], v[160:161]
	v_pk_mul_f32 v[34:35], v[34:35], v[162:163]
	v_pk_mul_f32 v[32:33], v[28:29], v[32:33]
	v_pk_mul_f32 v[34:35], v[30:31], v[34:35]
	v_pk_mul_f32 v[160:161], v[178:179], v[24:25] op_sel_hi:[0,1]
	v_pk_mul_f32 v[162:163], v[178:179], v[26:27] op_sel_hi:[0,1]
	v_exp_f32_e32 v160, v160
	v_exp_f32_e32 v161, v161
	v_exp_f32_e32 v162, v162
; __device__ __forceinline__ unsigned cvt_pk_bf16(float lo, float hi) { unsigned r; asm volatile("v_cvt_pk_bf16_f32 %0, %1, %2" : "=v"(r) : "v"(lo), "v"(hi)); return r; }
; __device__ __forceinline__ float fast_sigmoid(float x) { return __builtin_amdgcn_rcpf(1.0f + __expf(-x)); }
; __device__ __forceinline__ CArgs* kargs() { CArgs* p = (CArgs*)__builtin_amdgcn_kernarg_segment_ptr(); asm volatile("" : "+s"(p)); return p; }
;     __device__ __forceinline__ void operator()(const i32x4 (&acc)[2][2][4][2], const Unit& u, int wr, int wc, int fr, int fq) const {
;     ...
; #pragma unroll
;         for (int ai = 0; ai < 2; ++ai)
; #pragma unroll
;             for (int m = 0; m < 4; ++m) { const int row = row0 + ai * HALF + m * 16; const float ra = rav[ai][m]; bf16_t* rowp = H + (size_t)row * ldh + col0;
;                 float hv[8];
; #pragma unroll
;                 for (int j = 0; j < 4; ++j) { const float g0 = (float)acc[ai][0][m][0][j] * ra * dg0[j], u0 = (float)acc[ai][1][m][0][j] * ra * du0[j]; hv[j] = g0 * fast_sigmoid(g0) * u0;
;                     const float g1 = (float)acc[ai][0][m][1][j] * ra * dg1[j], u1 = (float)acc[ai][1][m][1][j] * ra * du1[j]; hv[4 + j] = g1 * fast_sigmoid(g1) * u1; }
;                 u32x4 w; w.x = cvt_pk_bf16(hv[0], hv[1]); w.y = cvt_pk_bf16(hv[2], hv[3]); w.z = cvt_pk_bf16(hv[4], hv[5]); w.w = cvt_pk_bf16(hv[6], hv[7]);
;                 *(u32x4*)rowp = w; }
; __global__ void __launch_bounds__(NWAVES * 64, 2) fwd_kernel(Args args_unused) {
;     ...
;         { constexpr int NU_F = (M / 256) * (NGU / 256); const int heavy = NU_F % G;
;           { CArgs* ka = kargs(); unsigned char* ws = ka->ws; int Kp = PLE; asm volatile("" : "+s"(Kp)); pg8::Gemm g{(bf16*)(ws + WS_PBF), (bf16*)(ws + WS_WPP), M, D, Kp}; pg8::StaticOrder S; pg8::EpiStoreBf16 E{(bf16*)(ws + WS_PP), D};
;             if (heavy > 0 && heavy < G) { const int npp = (M / 256) * (D / 256), cut = (npp * 3 / 4) / (G - heavy) * (G - heavy);
;                 if (bx >= heavy) { S.init(M, D, G - heavy, bx - heavy); S.lim = cut; } else { S.init(M, D, heavy, bx); S.base = cut; } }
;             else S.init(M, D, G, bx);
	v_exp_f32_e32 v163, v163
	v_pk_add_f32 v[160:161], v[178:179], v[160:161] op_sel:[1,0] op_sel_hi:[1,1]
	v_pk_add_f32 v[162:163], v[178:179], v[162:163] op_sel:[1,0] op_sel_hi:[1,1]
	v_rcp_f32_e32 v160, v160
	v_rcp_f32_e32 v161, v161
	v_rcp_f32_e32 v162, v162
	v_rcp_f32_e32 v163, v163
	v_pk_mul_f32 v[24:25], v[24:25], v[160:161]
	v_pk_mul_f32 v[26:27], v[26:27], v[162:163]
	v_pk_mul_f32 v[24:25], v[20:21], v[24:25]
	v_pk_mul_f32 v[26:27], v[22:23], v[26:27]
	v_cvt_pk_bf16_f32 v32, v32, v33
	v_cvt_pk_bf16_f32 v33, v34, v35
	v_cvt_pk_bf16_f32 v34, v24, v25
	v_cvt_pk_bf16_f32 v35, v26, v27
	v_add_u32_e32 v187, 0x35c000, v186
	global_store_dwordx4 v187, v[32:35], s[14:15]
	v_pk_mul_f32 v[16:17], v[158:159], v[16:17] op_sel_hi:[0,1]
	v_pk_mul_f32 v[12:13], v[158:159], v[12:13] op_sel_hi:[0,1]
	v_pk_mul_f32 v[18:19], v[158:159], v[18:19] op_sel_hi:[0,1]
	v_pk_mul_f32 v[14:15], v[158:159], v[14:15] op_sel_hi:[0,1]
	v_pk_mul_f32 v[8:9], v[158:159], v[8:9] op_sel_hi:[0,1]
	v_pk_mul_f32 v[4:5], v[158:159], v[4:5] op_sel_hi:[0,1]
	v_pk_mul_f32 v[10:11], v[158:159], v[10:11] op_sel_hi:[0,1]
	v_pk_mul_f32 v[6:7], v[158:159], v[6:7] op_sel_hi:[0,1]
	v_pk_mul_f32 v[16:17], v[44:45], v[16:17]
	v_pk_mul_f32 v[12:13], v[144:145], v[12:13]
	v_pk_mul_f32 v[18:19], v[46:47], v[18:19]
	v_pk_mul_f32 v[14:15], v[146:147], v[14:15]
	v_pk_mul_f32 v[8:9], v[36:37], v[8:9]
	v_pk_mul_f32 v[4:5], v[140:141], v[4:5]
	v_pk_mul_f32 v[10:11], v[38:39], v[10:11]
	v_pk_mul_f32 v[6:7], v[142:143], v[6:7]
	v_pk_mul_f32 v[160:161], v[178:179], v[16:17] op_sel_hi:[0,1]
	v_pk_mul_f32 v[162:163], v[178:179], v[18:19] op_sel_hi:[0,1]
	v_exp_f32_e32 v160, v160
	v_exp_f32_e32 v161, v161
	v_exp_f32_e32 v162, v162
	v_exp_f32_e32 v163, v163
	v_pk_add_f32 v[160:161], v[178:179], v[160:161] op_sel:[1,0] op_sel_hi:[1,1]
	v_pk_add_f32 v[162:163], v[178:179], v[162:163] op_sel:[1,0] op_sel_hi:[1,1]
	v_rcp_f32_e32 v160, v160
	v_rcp_f32_e32 v161, v161
	v_rcp_f32_e32 v162, v162
	v_rcp_f32_e32 v163, v163
	v_pk_mul_f32 v[16:17], v[16:17], v[160:161]
	v_pk_mul_f32 v[18:19], v[18:19], v[162:163]
	v_pk_mul_f32 v[16:17], v[12:13], v[16:17]
	v_pk_mul_f32 v[18:19], v[14:15], v[18:19]
	v_pk_mul_f32 v[160:161], v[178:179], v[8:9] op_sel_hi:[0,1]
	v_pk_mul_f32 v[162:163], v[178:179], v[10:11] op_sel_hi:[0,1]
	v_exp_f32_e32 v160, v160
	v_exp_f32_e32 v161, v161
	v_exp_f32_e32 v162, v162
	v_exp_f32_e32 v163, v163
	v_pk_add_f32 v[160:161], v[178:179], v[160:161] op_sel:[1,0] op_sel_hi:[1,1]
	v_pk_add_f32 v[162:163], v[178:179], v[162:163] op_sel:[1,0] op_sel_hi:[1,1]
	v_rcp_f32_e32 v160, v160
	v_rcp_f32_e32 v161, v161
	v_rcp_f32_e32 v162, v162
	v_rcp_f32_e32 v163, v163
	v_pk_mul_f32 v[8:9], v[8:9], v[160:161]
	v_pk_mul_f32 v[10:11], v[10:11], v[162:163]
	v_pk_mul_f32 v[8:9], v[4:5], v[8:9]
	v_pk_mul_f32 v[10:11], v[6:7], v[10:11]
	v_cvt_pk_bf16_f32 v16, v16, v17
	v_cvt_pk_bf16_f32 v17, v18, v19
	v_cvt_pk_bf16_f32 v18, v8, v9
	v_cvt_pk_bf16_f32 v19, v10, v11
	v_add_u32_e32 v187, 0x3b2000, v186
	global_store_dwordx4 v187, v[16:19], s[14:15]
	s_mov_b32 s67, 0x40000
	s_mov_b64 s[34:35], -1
	s_andn2_b64 vcc, exec, s[10:11]
	s_cbranch_vccnz .LBB0_1587
	s_andn2_b64 vcc, exec, s[12:13]
	s_cbranch_vccnz .LBB0_1586
	s_branch .LBB0_1586
.LBB0_1597:
	s_waitcnt vmcnt(0)
	s_and_b64 vcc, exec, s[20:21]
	s_cbranch_vccz .Lnoalign_3
	s_barrier
.Lnoalign_3:
	s_barrier
.LBB0_1598:
	v_readlane_b32 s34, v254, 54
	s_abs_i32 s11, s34
	v_cvt_f32_u32_e32 v2, s11
	s_sub_i32 s14, 0, s11
	v_readlane_b32 s12, v254, 0
	v_readlane_b32 s13, v254, 1
	v_rcp_iflag_f32_e32 v2, v2
	s_load_dwordx2 s[12:13], s[12:13], 0x98
	s_movk_i32 s10, 0x100
	v_mul_f32_e32 v2, 0x4f7ffffe, v2
	v_cvt_u32_f32_e32 v2, v2
	s_nop 0
	v_readfirstlane_b32 s15, v2
	s_mul_i32 s14, s14, s15
	s_mul_hi_u32 s14, s15, s14
	s_add_i32 s15, s15, s14
	s_mul_hi_u32 s14, s15, 0x1580
	s_mul_i32 s14, s14, s11
	s_sub_i32 s14, 0x1580, s14
	s_sub_i32 s15, s14, s11
	s_cmp_ge_u32 s14, s11
	s_cselect_b32 s14, s15, s14
	s_sub_i32 s15, s14, s11
	s_cmp_ge_u32 s14, s11
	s_cselect_b32 s11, s15, s14
	s_cmp_eq_u32 s11, 0
	s_cselect_b64 s[14:15], -1, 0
	s_cmp_lt_i32 s34, 0
	s_cselect_b64 s[16:17], -1, 0
	s_or_b64 s[14:15], s[16:17], s[14:15]
	s_and_b64 vcc, exec, s[14:15]
	s_cbranch_vccnz .LBB0_1600
	s_sub_i32 s14, s34, s11
	s_abs_i32 s16, s14
	v_cvt_f32_u32_e32 v2, s16
	s_sub_i32 s17, 0, s16
	s_mov_b32 s15, s29
	v_rcp_iflag_f32_e32 v2, v2
	s_nop 0
	v_mul_f32_e32 v2, 0x4f7ffffe, v2
	v_cvt_u32_f32_e32 v2, v2
	s_nop 0
	v_readfirstlane_b32 s18, v2
	s_mul_i32 s17, s17, s18
	s_mul_hi_u32 s17, s18, s17
	s_add_i32 s18, s18, s17
	s_mul_hi_u32 s17, s18, 0x300
	s_mul_i32 s17, s17, s16
	s_sub_i32 s17, 0x300, s17
	s_sub_i32 s18, s17, s16
	s_cmp_ge_u32 s17, s16
	s_cselect_b32 s17, s18, s17
	s_sub_i32 s18, s17, s16
	s_cmp_ge_u32 s17, s16
	s_cselect_b32 s16, s18, s17
	s_sub_i32 s16, 0x300, s16
	s_cmp_lt_i32 s2, s11
	s_cselect_b32 s34, s11, s14
	s_cselect_b32 s11, 0, s11
	s_cselect_b32 s28, s16, 0
	s_cselect_b32 s14, 0x400, s16
	s_sub_i32 s16, s2, s11
	s_ashr_i32 s17, s16, 31
	s_mov_b64 s[18:19], s[28:29]
	s_branch .LBB0_1601

; __device__ __forceinline__ unsigned cvt_pk_bf16(float lo, float hi) { unsigned r; asm volatile("v_cvt_pk_bf16_f32 %0, %1, %2" : "=v"(r) : "v"(lo), "v"(hi)); return r; }
;     __device__ __forceinline__ void operator()(const f32x4 (&acc)[2][2][4][2], const Unit& u, int wr, int wc, int fr, int fq) const {
;         const int row0 = u.pm * BM + wr * 64 + fr, col0 = u.pn * BM + wc * 32 + 8 * fq;
; #pragma unroll
;         for (int ai = 0; ai < 2; ++ai)
; #pragma unroll
;             for (int m = 0; m < 4; ++m) { bf16_t* rowp = O + (size_t)(row0 + ai * HALF + m * 16) * ldc + col0;
; #pragma unroll
;                 for (int bj = 0; bj < 2; ++bj) { const f32x4 v0 = acc[ai][bj][m][0], v1 = acc[ai][bj][m][1];
;                     u32x4 w; w.x = cvt_pk_bf16(v0[0], v0[1]); w.y = cvt_pk_bf16(v0[2], v0[3]); w.z = cvt_pk_bf16(v1[0], v1[1]); w.w = cvt_pk_bf16(v1[2], v1[3]);
;                     *(u32x4*)(rowp + bj * HALF) = w; } }
;     }
; __device__ __forceinline__ void xcd_barrier(const XcdBarrier& b) {
;     asm volatile("s_waitcnt vmcnt(0)" ::: "memory");
;     __syncthreads();
;     if (threadIdx.x == 0) {
;         unsigned* bar = b.bar;
;         __builtin_amdgcn_s_waitcnt(0);
;         unsigned nloc = b.st[0], nx = b.st[1];
;         if (nloc == 0u) { xcd_barrier_complete(bar, b.x, nloc, nx); b.st[0] = nloc; b.st[1] = nx; }
.LBB0_1625:
.LBB0_1627:
	v_lshl_add_u32 v146, s54, 8, v142
	v_lshl_or_b32 v148, s60, 8, v144
	v_ashrrev_i32_e32 v147, 31, v146
	v_ashrrev_i32_e32 v149, 31, v148
	v_lshlrev_b64 v[150:151], 13, v[146:147]
	v_lshl_add_u64 v[150:151], s[24:25], 0, v[150:151]
	v_lshlrev_b64 v[148:149], 1, v[148:149]
	v_lshl_add_u64 v[150:151], v[150:151], 0, v[148:149]
	v_cvt_pk_bf16_f32 v124, v124, v125
	v_cvt_pk_bf16_f32 v125, v126, v127
	v_cvt_pk_bf16_f32 v126, v128, v129
	v_cvt_pk_bf16_f32 v127, v130, v131
	global_store_dwordx4 v[150:151], v[124:127], off
	v_cvt_pk_bf16_f32 v120, v120, v121
	v_cvt_pk_bf16_f32 v121, v122, v123
	v_cvt_pk_bf16_f32 v122, v116, v117
	v_or_b32_e32 v116, 16, v146
	v_ashrrev_i32_e32 v117, 31, v116
	v_lshlrev_b64 v[116:117], 13, v[116:117]
	v_lshl_add_u64 v[116:117], s[24:25], 0, v[116:117]
	v_lshl_add_u64 v[116:117], v[116:117], 0, v[148:149]
	v_cvt_pk_bf16_f32 v123, v118, v119
	global_store_dwordx4 v[150:151], v[120:123], off offset:256
	v_cvt_pk_bf16_f32 v112, v112, v113
	v_cvt_pk_bf16_f32 v113, v114, v115
	v_cvt_pk_bf16_f32 v114, v108, v109
	v_cvt_pk_bf16_f32 v115, v110, v111
	global_store_dwordx4 v[116:117], v[112:115], off
	v_cvt_pk_bf16_f32 v104, v104, v105
	v_cvt_pk_bf16_f32 v105, v106, v107
	v_cvt_pk_bf16_f32 v106, v100, v101
	v_or_b32_e32 v100, 32, v146
	v_ashrrev_i32_e32 v101, 31, v100
	v_lshlrev_b64 v[100:101], 13, v[100:101]
	v_lshl_add_u64 v[100:101], s[24:25], 0, v[100:101]
	v_lshl_add_u64 v[100:101], v[100:101], 0, v[148:149]
	v_cvt_pk_bf16_f32 v107, v102, v103
	global_store_dwordx4 v[116:117], v[104:107], off offset:256
	v_cvt_pk_bf16_f32 v96, v96, v97
	v_cvt_pk_bf16_f32 v97, v98, v99
	v_cvt_pk_bf16_f32 v98, v92, v93
	v_cvt_pk_bf16_f32 v99, v94, v95
	global_store_dwordx4 v[100:101], v[96:99], off
	v_cvt_pk_bf16_f32 v88, v88, v89
	v_cvt_pk_bf16_f32 v89, v90, v91
	v_cvt_pk_bf16_f32 v90, v84, v85
	v_or_b32_e32 v84, 48, v146
	v_ashrrev_i32_e32 v85, 31, v84
	v_lshlrev_b64 v[84:85], 13, v[84:85]
	v_lshl_add_u64 v[84:85], s[24:25], 0, v[84:85]
	v_lshl_add_u64 v[84:85], v[84:85], 0, v[148:149]
	s_mov_b32 s38, 0x100000
	v_cvt_pk_bf16_f32 v91, v86, v87
	global_store_dwordx4 v[100:101], v[88:91], off offset:256
	v_cvt_pk_bf16_f32 v80, v80, v81
	v_cvt_pk_bf16_f32 v81, v82, v83
	v_cvt_pk_bf16_f32 v82, v76, v77
	v_cvt_pk_bf16_f32 v83, v78, v79
	global_store_dwordx4 v[84:85], v[80:83], off
	v_cvt_pk_bf16_f32 v72, v72, v73
	v_cvt_pk_bf16_f32 v73, v74, v75
	v_cvt_pk_bf16_f32 v74, v68, v69
	v_cvt_pk_bf16_f32 v75, v70, v71
	global_store_dwordx4 v[84:85], v[72:75], off offset:256
	s_mov_b64 s[44:45], 0x100000
	v_cvt_pk_bf16_f32 v64, v64, v65
	v_cvt_pk_bf16_f32 v65, v66, v67
	v_cvt_pk_bf16_f32 v66, v60, v61
	v_add_co_u32_e32 v60, vcc, s38, v150
	v_lshl_add_u64 v[68:69], v[150:151], 0, s[44:45]
	s_nop 0
	v_addc_co_u32_e32 v61, vcc, 0, v151, vcc
	s_mov_b64 s[44:45], 0x120000
	v_cvt_pk_bf16_f32 v67, v62, v63
	global_store_dwordx4 v[60:61], v[64:67], off
	v_cvt_pk_bf16_f32 v56, v56, v57
	v_cvt_pk_bf16_f32 v57, v58, v59
	v_cvt_pk_bf16_f32 v58, v52, v53
	v_lshl_add_u64 v[52:53], v[150:151], 0, s[44:45]
	s_mov_b32 s44, 0x120000
	v_cvt_pk_bf16_f32 v59, v54, v55
	global_store_dwordx4 v[68:69], v[56:59], off offset:256
	v_cvt_pk_bf16_f32 v48, v48, v49
	v_cvt_pk_bf16_f32 v49, v50, v51
	v_cvt_pk_bf16_f32 v50, v44, v45
	v_add_co_u32_e32 v44, vcc, s44, v150
	s_mov_b64 s[44:45], 0x140000
	s_nop 0
	v_addc_co_u32_e32 v45, vcc, 0, v151, vcc
	v_cvt_pk_bf16_f32 v51, v46, v47
	global_store_dwordx4 v[44:45], v[48:51], off
	v_cvt_pk_bf16_f32 v40, v40, v41
	v_cvt_pk_bf16_f32 v41, v42, v43
	v_cvt_pk_bf16_f32 v42, v36, v37
	v_lshl_add_u64 v[36:37], v[150:151], 0, s[44:45]
	s_mov_b32 s44, 0x140000
	v_cvt_pk_bf16_f32 v43, v38, v39
	global_store_dwordx4 v[52:53], v[40:43], off offset:256
	v_cvt_pk_bf16_f32 v32, v32, v33
	v_cvt_pk_bf16_f32 v33, v34, v35
	v_cvt_pk_bf16_f32 v34, v28, v29
	v_add_co_u32_e32 v28, vcc, s44, v150
	v_cvt_pk_bf16_f32 v35, v30, v31
	s_mov_b64 s[44:45], 0x160000
	s_nop 0
	v_addc_co_u32_e32 v29, vcc, 0, v151, vcc
	global_store_dwordx4 v[28:29], v[32:35], off
	v_cvt_pk_bf16_f32 v24, v24, v25
	v_cvt_pk_bf16_f32 v25, v26, v27
	v_cvt_pk_bf16_f32 v26, v20, v21
	v_cvt_pk_bf16_f32 v27, v22, v23
	global_store_dwordx4 v[36:37], v[24:27], off offset:256
	v_cvt_pk_bf16_f32 v16, v16, v17
	v_cvt_pk_bf16_f32 v17, v18, v19
	v_cvt_pk_bf16_f32 v18, v12, v13
	v_add_co_u32_e32 v12, vcc, 0x160000, v150
	v_lshl_add_u64 v[20:21], v[150:151], 0, s[44:45]
	s_nop 0
	v_addc_co_u32_e32 v13, vcc, 0, v151, vcc
	s_and_b64 vcc, exec, s[10:11]
	s_mov_b64 s[10:11], -1
	v_cvt_pk_bf16_f32 v19, v14, v15
	global_store_dwordx4 v[12:13], v[16:19], off
	v_cvt_pk_bf16_f32 v8, v8, v9
	v_cvt_pk_bf16_f32 v9, v10, v11
	v_cvt_pk_bf16_f32 v10, v4, v5
	v_cvt_pk_bf16_f32 v11, v6, v7
	global_store_dwordx4 v[20:21], v[8:11], off offset:256
	s_cbranch_vccnz .LBB0_1610
	s_andn2_b64 vcc, exec, s[22:23]
	s_cbranch_vccnz .LBB0_1609
	s_branch .LBB0_1609
.LBB0_1630:
	s_waitcnt vmcnt(0)
	s_and_b64 vcc, exec, s[36:37]
	s_cbranch_vccz .Lnoalign_4
	s_barrier
.Lnoalign_4:
	s_barrier
.LBB0_1631:
	s_waitcnt lgkmcnt(0)
	v_readlane_b32 s12, v254, 0
	v_readlane_b32 s13, v254, 1
	s_getreg_b32 s14, hwreg(HW_REG_XCC_ID, 0, 4)
	s_waitcnt vmcnt(0)
	s_waitcnt vmcnt(0)
	s_barrier
	s_mov_b64 s[10:11], exec
	v_readlane_b32 s16, v254, 2
	v_readlane_b32 s17, v254, 3
	s_and_b64 s[16:17], s[10:11], s[16:17]
	s_mov_b64 exec, s[16:17]
	s_cbranch_execz .LBB0_1683
	v_readlane_b32 s15, v254, 39
	s_load_dwordx2 s[12:13], s[12:13], 0x98
	s_waitcnt vmcnt(0) expcnt(0) lgkmcnt(0)
	v_mov_b32_e32 v2, s15
	ds_read_b32 v5, v2
	v_readlane_b32 s15, v254, 40
	s_and_b32 s28, s14, 15
	s_waitcnt lgkmcnt(0)
	v_cmp_ne_u32_e32 vcc, 0, v5
	v_mov_b32_e32 v2, s15
	ds_read_b32 v4, v2
	s_cbranch_vccnz .LBB0_1647
	v_readlane_b32 s14, v254, 4
	v_readlane_b32 s15, v254, 5
	s_load_dwordx2 s[18:19], s[14:15], 0x4
	s_add_u32 s14, s12, 0x4200
	s_addc_u32 s15, s13, 0
	s_add_u32 s16, s12, 0x4400
	s_addc_u32 s17, s13, 0
	v_readlane_b32 s20, v254, 54
	s_waitcnt lgkmcnt(0)
	s_mul_i32 s42, s18, s20
	s_add_u32 s18, s12, 0x4500
	s_mul_i32 s42, s42, s19
	s_addc_u32 s19, s13, 0
	s_add_u32 s20, s12, 0x4600
	s_addc_u32 s21, s13, 0
	s_add_u32 s22, s12, 0x4700
	s_addc_u32 s23, s13, 0
	s_add_u32 s24, s12, 0x4800
	s_addc_u32 s25, s13, 0
	s_add_u32 s26, s12, 0x4900
	s_addc_u32 s27, s13, 0
	s_add_u32 s36, s12, 0x4a00
	s_addc_u32 s37, s13, 0
	s_add_u32 s40, s12, 0x4b00
	s_addc_u32 s41, s13, 0
	s_add_u32 s44, s12, 0x4c00
	s_addc_u32 s45, s13, 0
	s_add_u32 s48, s12, 0x4d00
	s_addc_u32 s49, s13, 0
	s_add_u32 s50, s12, 0x4e00
	s_addc_u32 s51, s13, 0
	s_add_u32 s54, s12, 0x4f00
	s_addc_u32 s55, s13, 0
	s_add_u32 s56, s12, 0x5000
	s_addc_u32 s57, s13, 0
	s_add_u32 s52, s12, 0x5100
	s_addc_u32 s53, s13, 0
	s_add_u32 s34, s12, 0x5200
	s_addc_u32 s35, s13, 0
	s_add_u32 s58, s12, 0x5300
	s_addc_u32 s59, s13, 0
	s_mov_b32 s43, 1
	s_branch .LBB0_1635

; __device__ __forceinline__ unsigned cvt_pk_bf16(float lo, float hi) { unsigned r; asm volatile("v_cvt_pk_bf16_f32 %0, %1, %2" : "=v"(r) : "v"(lo), "v"(hi)); return r; }
;     __device__ __forceinline__ void operator()(const f32x4 (&acc)[2][2][4][2], const Unit& u, int wr, int wc, int fr, int fq) const {
;         const int row0 = u.pm * BM + wr * 64 + fr, col0 = u.pn * BM + wc * 32 + 8 * fq;
;         u32x4 xv[2][4][2];
; #pragma unroll
;         for (int ai = 0; ai < 2; ++ai)
; #pragma unroll
;             for (int m = 0; m < 4; ++m)
; #pragma unroll
;                 for (int bj = 0; bj < 2; ++bj) xv[ai][m][bj] = *(const u32x4*)(XB + (size_t)(row0 + ai * HALF + m * 16) * ldc + col0 + bj * HALF);
; #pragma unroll
;         for (int ai = 0; ai < 2; ++ai) {
; #pragma unroll
;             for (int m = 0; m < 4; ++m) { const int row = row0 + ai * HALF + m * 16;
; #pragma unroll
;                 for (int bj = 0; bj < 2; ++bj) { f32x4 v0, v1; unpack8(xv[ai][m][bj], v0, v1); v0 = v0 + acc[ai][bj][m][0]; v1 = v1 + acc[ai][bj][m][1];
;                     u32x4 w; w.x = cvt_pk_bf16(v0[0], v0[1]); w.y = cvt_pk_bf16(v0[2], v0[3]); w.z = cvt_pk_bf16(v1[0], v1[1]); w.w = cvt_pk_bf16(v1[2], v1[3]);
;                     *(u32x4*)(XB + (size_t)row * ldc + col0 + bj * HALF) = w; } }
.Lkloop_exit_5:
.LBB0_1703:
	v_lshl_or_b32 v126, s51, 8, v241
	v_lshl_add_u32 v124, s52, 8, v239
	v_ashrrev_i32_e32 v127, 31, v126
	v_lshlrev_b64 v[214:215], 1, v[126:127]
	v_ashrrev_i32_e32 v125, 31, v124
	v_lshl_add_u64 v[126:127], s[16:17], 0, v[214:215]
	v_lshlrev_b64 v[248:249], 13, v[124:125]
	v_lshl_add_u64 v[128:129], v[126:127], 0, v[248:249]
	global_load_dwordx4 v[244:247], v[128:129], off
	global_load_dwordx4 v[188:191], v[128:129], off offset:256
	v_or_b32_e32 v128, 16, v124
	v_ashrrev_i32_e32 v129, 31, v128
	v_lshlrev_b64 v[228:229], 13, v[128:129]
	v_lshl_add_u64 v[128:129], v[126:127], 0, v[228:229]
	global_load_dwordx4 v[184:187], v[128:129], off
	global_load_dwordx4 v[180:183], v[128:129], off offset:256
	v_or_b32_e32 v128, 32, v124
	v_ashrrev_i32_e32 v129, 31, v128
	v_lshlrev_b64 v[226:227], 13, v[128:129]
	v_lshl_add_u64 v[128:129], v[126:127], 0, v[226:227]
	global_load_dwordx4 v[176:179], v[128:129], off
	global_load_dwordx4 v[168:171], v[128:129], off offset:256
	v_or_b32_e32 v124, 48, v124
	v_ashrrev_i32_e32 v125, 31, v124
	v_lshlrev_b64 v[224:225], 13, v[124:125]
	v_lshl_add_u64 v[124:125], v[126:127], 0, v[224:225]
	global_load_dwordx4 v[172:175], v[124:125], off
	global_load_dwordx4 v[164:167], v[124:125], off offset:256
	s_mov_b64 s[22:23], 0x100000
	v_lshl_add_u64 v[222:223], v[248:249], 0, s[22:23]
	v_lshl_add_u64 v[124:125], v[126:127], 0, v[222:223]
	global_load_dwordx4 v[160:163], v[124:125], off
	global_load_dwordx4 v[156:159], v[124:125], off offset:256
	s_mov_b64 s[22:23], 0x120000
	v_lshl_add_u64 v[220:221], v[248:249], 0, s[22:23]
	v_lshl_add_u64 v[124:125], v[126:127], 0, v[220:221]
	global_load_dwordx4 v[152:155], v[124:125], off
	global_load_dwordx4 v[148:151], v[124:125], off offset:256
	s_mov_b64 s[22:23], 0x140000
	v_lshl_add_u64 v[218:219], v[248:249], 0, s[22:23]
	v_lshl_add_u64 v[124:125], v[126:127], 0, v[218:219]
	global_load_dwordx4 v[144:147], v[124:125], off
	global_load_dwordx4 v[132:135], v[124:125], off offset:256
	s_mov_b64 s[22:23], 0x160000
	v_lshl_add_u64 v[216:217], v[248:249], 0, s[22:23]
	v_lshl_add_u64 v[124:125], v[126:127], 0, v[216:217]
	global_load_dwordx4 v[128:131], v[124:125], off
	s_nop 0
	global_load_dwordx4 v[124:127], v[124:125], off offset:256
	s_mov_b64 s[22:23], -1
	s_and_b64 vcc, exec, s[10:11]
	s_waitcnt vmcnt(0)
	v_lshlrev_b32_e32 v250, 16, v244
	v_and_b32_e32 v251, 0xffff0000, v244
	v_lshlrev_b32_e32 v244, 16, v245
	v_and_b32_e32 v245, 0xffff0000, v245
	v_lshlrev_b32_e32 v252, 16, v246
	v_and_b32_e32 v253, 0xffff0000, v246
	v_lshlrev_b32_e32 v246, 16, v247
	v_and_b32_e32 v247, 0xffff0000, v247
	v_pk_add_f32 v[140:141], v[140:141], v[250:251]
	v_pk_add_f32 v[142:143], v[142:143], v[244:245]
	v_pk_add_f32 v[244:245], v[138:139], v[246:247]
	v_pk_add_f32 v[138:139], v[136:137], v[252:253]
	v_cvt_pk_bf16_f32 v136, v140, v141
	v_lshl_add_u64 v[140:141], s[16:17], 0, v[248:249]
	v_cvt_pk_bf16_f32 v137, v142, v143
	v_cvt_pk_bf16_f32 v138, v138, v139
	v_cvt_pk_bf16_f32 v139, v244, v245
	v_lshl_add_u64 v[140:141], v[140:141], 0, v[214:215]
	global_store_dwordx4 v[140:141], v[136:139], off
	v_lshlrev_b32_e32 v142, 16, v190
	v_and_b32_e32 v143, 0xffff0000, v190
	v_lshlrev_b32_e32 v136, 16, v188
	v_and_b32_e32 v137, 0xffff0000, v188
	v_lshlrev_b32_e32 v138, 16, v189
	v_and_b32_e32 v139, 0xffff0000, v189
	v_lshlrev_b32_e32 v188, 16, v191
	v_and_b32_e32 v189, 0xffff0000, v191
	v_pk_add_f32 v[122:123], v[122:123], v[138:139]
	v_pk_add_f32 v[120:121], v[120:121], v[136:137]
	v_pk_add_f32 v[136:137], v[118:119], v[188:189]
	v_pk_add_f32 v[118:119], v[116:117], v[142:143]
	v_cvt_pk_bf16_f32 v116, v120, v121
	v_cvt_pk_bf16_f32 v117, v122, v123
	v_lshlrev_b32_e32 v120, 16, v186
	v_cvt_pk_bf16_f32 v118, v118, v119
	v_cvt_pk_bf16_f32 v119, v136, v137
	global_store_dwordx4 v[140:141], v[116:119], off offset:256
	v_and_b32_e32 v121, 0xffff0000, v186
	v_lshlrev_b32_e32 v122, 16, v187
	v_lshlrev_b32_e32 v116, 16, v184
	v_and_b32_e32 v117, 0xffff0000, v184
	v_and_b32_e32 v123, 0xffff0000, v187
	v_pk_add_f32 v[112:113], v[112:113], v[116:117]
	v_lshlrev_b32_e32 v118, 16, v185
	v_and_b32_e32 v119, 0xffff0000, v185
	v_pk_add_f32 v[116:117], v[110:111], v[122:123]
	v_pk_add_f32 v[110:111], v[108:109], v[120:121]
	v_cvt_pk_bf16_f32 v108, v112, v113
	v_lshl_add_u64 v[112:113], s[16:17], 0, v[228:229]
	v_pk_add_f32 v[114:115], v[114:115], v[118:119]
	v_lshl_add_u64 v[112:113], v[112:113], 0, v[214:215]
	v_cvt_pk_bf16_f32 v109, v114, v115
	v_cvt_pk_bf16_f32 v110, v110, v111
	v_cvt_pk_bf16_f32 v111, v116, v117
	global_store_dwordx4 v[112:113], v[108:111], off
	v_lshlrev_b32_e32 v114, 16, v182
	v_and_b32_e32 v115, 0xffff0000, v182
	v_lshlrev_b32_e32 v108, 16, v180
	v_and_b32_e32 v109, 0xffff0000, v180
	v_lshlrev_b32_e32 v110, 16, v181
	v_and_b32_e32 v111, 0xffff0000, v181
	v_lshlrev_b32_e32 v116, 16, v183
	v_and_b32_e32 v117, 0xffff0000, v183
	v_pk_add_f32 v[106:107], v[106:107], v[110:111]
	v_pk_add_f32 v[104:105], v[104:105], v[108:109]
	v_pk_add_f32 v[108:109], v[102:103], v[116:117]
	v_pk_add_f32 v[102:103], v[100:101], v[114:115]
	v_cvt_pk_bf16_f32 v100, v104, v105
	v_cvt_pk_bf16_f32 v101, v106, v107
	v_lshlrev_b32_e32 v104, 16, v178
	v_cvt_pk_bf16_f32 v102, v102, v103
	v_cvt_pk_bf16_f32 v103, v108, v109
	global_store_dwordx4 v[112:113], v[100:103], off offset:256
	v_and_b32_e32 v105, 0xffff0000, v178
	v_lshlrev_b32_e32 v106, 16, v179
	v_lshlrev_b32_e32 v100, 16, v176
	v_and_b32_e32 v101, 0xffff0000, v176
	v_and_b32_e32 v107, 0xffff0000, v179
	v_pk_add_f32 v[96:97], v[96:97], v[100:101]
	v_lshlrev_b32_e32 v102, 16, v177
	v_and_b32_e32 v103, 0xffff0000, v177
	v_pk_add_f32 v[100:101], v[94:95], v[106:107]
; __device__ __forceinline__ unsigned cvt_pk_bf16(float lo, float hi) { unsigned r; asm volatile("v_cvt_pk_bf16_f32 %0, %1, %2" : "=v"(r) : "v"(lo), "v"(hi)); return r; }
;     __device__ __forceinline__ void operator()(const f32x4 (&acc)[2][2][4][2], const Unit& u, int wr, int wc, int fr, int fq) const {
;         const int row0 = u.pm * BM + wr * 64 + fr, col0 = u.pn * BM + wc * 32 + 8 * fq;
;         u32x4 xv[2][4][2];
; #pragma unroll
;         for (int ai = 0; ai < 2; ++ai)
; #pragma unroll
;             for (int m = 0; m < 4; ++m)
; #pragma unroll
;                 for (int bj = 0; bj < 2; ++bj) xv[ai][m][bj] = *(const u32x4*)(XB + (size_t)(row0 + ai * HALF + m * 16) * ldc + col0 + bj * HALF);
; #pragma unroll
;         for (int ai = 0; ai < 2; ++ai) {
; #pragma unroll
;             for (int m = 0; m < 4; ++m) { const int row = row0 + ai * HALF + m * 16;
; #pragma unroll
;                 for (int bj = 0; bj < 2; ++bj) { f32x4 v0, v1; unpack8(xv[ai][m][bj], v0, v1); v0 = v0 + acc[ai][bj][m][0]; v1 = v1 + acc[ai][bj][m][1];
;                     u32x4 w; w.x = cvt_pk_bf16(v0[0], v0[1]); w.y = cvt_pk_bf16(v0[2], v0[3]); w.z = cvt_pk_bf16(v1[0], v1[1]); w.w = cvt_pk_bf16(v1[2], v1[3]);
;                     *(u32x4*)(XB + (size_t)row * ldc + col0 + bj * HALF) = w; } }
	v_pk_add_f32 v[94:95], v[92:93], v[104:105]
	v_cvt_pk_bf16_f32 v92, v96, v97
	v_lshl_add_u64 v[96:97], s[16:17], 0, v[226:227]
	v_pk_add_f32 v[98:99], v[98:99], v[102:103]
	v_lshl_add_u64 v[96:97], v[96:97], 0, v[214:215]
	v_cvt_pk_bf16_f32 v93, v98, v99
	v_cvt_pk_bf16_f32 v94, v94, v95
	v_cvt_pk_bf16_f32 v95, v100, v101
	global_store_dwordx4 v[96:97], v[92:95], off
	v_lshlrev_b32_e32 v98, 16, v170
	v_and_b32_e32 v99, 0xffff0000, v170
	v_lshlrev_b32_e32 v92, 16, v168
	v_and_b32_e32 v93, 0xffff0000, v168
	v_lshlrev_b32_e32 v94, 16, v169
	v_and_b32_e32 v95, 0xffff0000, v169
	v_lshlrev_b32_e32 v100, 16, v171
	v_and_b32_e32 v101, 0xffff0000, v171
	v_pk_add_f32 v[90:91], v[90:91], v[94:95]
	v_pk_add_f32 v[88:89], v[88:89], v[92:93]
	v_pk_add_f32 v[92:93], v[86:87], v[100:101]
	v_pk_add_f32 v[86:87], v[84:85], v[98:99]
	v_cvt_pk_bf16_f32 v84, v88, v89
	v_cvt_pk_bf16_f32 v85, v90, v91
	v_lshlrev_b32_e32 v88, 16, v174
	v_cvt_pk_bf16_f32 v86, v86, v87
	v_cvt_pk_bf16_f32 v87, v92, v93
	global_store_dwordx4 v[96:97], v[84:87], off offset:256
	v_and_b32_e32 v89, 0xffff0000, v174
	v_lshlrev_b32_e32 v90, 16, v175
	v_lshlrev_b32_e32 v84, 16, v172
	v_and_b32_e32 v85, 0xffff0000, v172
	v_and_b32_e32 v91, 0xffff0000, v175
	v_pk_add_f32 v[80:81], v[80:81], v[84:85]
	v_lshlrev_b32_e32 v86, 16, v173
	v_and_b32_e32 v87, 0xffff0000, v173
	v_pk_add_f32 v[84:85], v[78:79], v[90:91]
	v_pk_add_f32 v[78:79], v[76:77], v[88:89]
	v_cvt_pk_bf16_f32 v76, v80, v81
	v_lshl_add_u64 v[80:81], s[16:17], 0, v[224:225]
	v_pk_add_f32 v[82:83], v[82:83], v[86:87]
	v_lshl_add_u64 v[80:81], v[80:81], 0, v[214:215]
	v_cvt_pk_bf16_f32 v77, v82, v83
	v_cvt_pk_bf16_f32 v78, v78, v79
	v_cvt_pk_bf16_f32 v79, v84, v85
	global_store_dwordx4 v[80:81], v[76:79], off
	v_lshlrev_b32_e32 v82, 16, v166
	v_and_b32_e32 v83, 0xffff0000, v166
	v_lshlrev_b32_e32 v76, 16, v164
	v_and_b32_e32 v77, 0xffff0000, v164
	v_lshlrev_b32_e32 v78, 16, v165
	v_and_b32_e32 v79, 0xffff0000, v165
	v_lshlrev_b32_e32 v84, 16, v167
	v_and_b32_e32 v85, 0xffff0000, v167
	v_pk_add_f32 v[74:75], v[74:75], v[78:79]
	v_pk_add_f32 v[72:73], v[72:73], v[76:77]
	v_pk_add_f32 v[76:77], v[70:71], v[84:85]
	v_pk_add_f32 v[70:71], v[68:69], v[82:83]
	v_cvt_pk_bf16_f32 v68, v72, v73
	v_cvt_pk_bf16_f32 v69, v74, v75
	v_lshlrev_b32_e32 v72, 16, v162
	v_cvt_pk_bf16_f32 v70, v70, v71
	v_cvt_pk_bf16_f32 v71, v76, v77
	global_store_dwordx4 v[80:81], v[68:71], off offset:256
	v_and_b32_e32 v73, 0xffff0000, v162
	v_lshlrev_b32_e32 v74, 16, v163
	v_lshlrev_b32_e32 v68, 16, v160
	v_and_b32_e32 v69, 0xffff0000, v160
	v_and_b32_e32 v75, 0xffff0000, v163
	v_pk_add_f32 v[64:65], v[64:65], v[68:69]
	v_lshlrev_b32_e32 v70, 16, v161
	v_and_b32_e32 v71, 0xffff0000, v161
	v_pk_add_f32 v[68:69], v[62:63], v[74:75]
	v_pk_add_f32 v[62:63], v[60:61], v[72:73]
	v_cvt_pk_bf16_f32 v60, v64, v65
	v_lshl_add_u64 v[64:65], s[16:17], 0, v[222:223]
	v_pk_add_f32 v[66:67], v[66:67], v[70:71]
	v_lshl_add_u64 v[64:65], v[64:65], 0, v[214:215]
	v_cvt_pk_bf16_f32 v61, v66, v67
	v_cvt_pk_bf16_f32 v62, v62, v63
	v_cvt_pk_bf16_f32 v63, v68, v69
	global_store_dwordx4 v[64:65], v[60:63], off
	v_lshlrev_b32_e32 v66, 16, v158
	v_and_b32_e32 v67, 0xffff0000, v158
	v_lshlrev_b32_e32 v60, 16, v156
	v_and_b32_e32 v61, 0xffff0000, v156
	v_lshlrev_b32_e32 v62, 16, v157
	v_and_b32_e32 v63, 0xffff0000, v157
	v_lshlrev_b32_e32 v68, 16, v159
	v_and_b32_e32 v69, 0xffff0000, v159
	v_pk_add_f32 v[58:59], v[58:59], v[62:63]
	v_pk_add_f32 v[56:57], v[56:57], v[60:61]
	v_pk_add_f32 v[60:61], v[54:55], v[68:69]
	v_pk_add_f32 v[54:55], v[52:53], v[66:67]
	v_cvt_pk_bf16_f32 v52, v56, v57
	v_cvt_pk_bf16_f32 v53, v58, v59
	v_lshlrev_b32_e32 v56, 16, v154
	v_cvt_pk_bf16_f32 v54, v54, v55
	v_cvt_pk_bf16_f32 v55, v60, v61
	global_store_dwordx4 v[64:65], v[52:55], off offset:256
	v_and_b32_e32 v57, 0xffff0000, v154
	v_lshlrev_b32_e32 v58, 16, v155
	v_lshlrev_b32_e32 v52, 16, v152
	v_and_b32_e32 v53, 0xffff0000, v152
	v_and_b32_e32 v59, 0xffff0000, v155
	v_pk_add_f32 v[48:49], v[48:49], v[52:53]
	v_lshlrev_b32_e32 v54, 16, v153
	v_and_b32_e32 v55, 0xffff0000, v153
	v_pk_add_f32 v[52:53], v[46:47], v[58:59]
	v_pk_add_f32 v[46:47], v[44:45], v[56:57]
	v_cvt_pk_bf16_f32 v44, v48, v49
	v_lshl_add_u64 v[48:49], s[16:17], 0, v[220:221]
	v_pk_add_f32 v[50:51], v[50:51], v[54:55]
	v_lshl_add_u64 v[48:49], v[48:49], 0, v[214:215]
	v_cvt_pk_bf16_f32 v45, v50, v51
	v_cvt_pk_bf16_f32 v46, v46, v47
	v_cvt_pk_bf16_f32 v47, v52, v53
	global_store_dwordx4 v[48:49], v[44:47], off
	v_lshlrev_b32_e32 v50, 16, v150
	v_and_b32_e32 v51, 0xffff0000, v150
	v_lshlrev_b32_e32 v44, 16, v148
	v_and_b32_e32 v45, 0xffff0000, v148
	v_lshlrev_b32_e32 v46, 16, v149
	v_and_b32_e32 v47, 0xffff0000, v149
	v_lshlrev_b32_e32 v52, 16, v151
	v_and_b32_e32 v53, 0xffff0000, v151
	v_pk_add_f32 v[42:43], v[42:43], v[46:47]
	v_pk_add_f32 v[40:41], v[40:41], v[44:45]
	v_pk_add_f32 v[44:45], v[38:39], v[52:53]
	v_pk_add_f32 v[38:39], v[36:37], v[50:51]
; __device__ __forceinline__ unsigned cvt_pk_bf16(float lo, float hi) { unsigned r; asm volatile("v_cvt_pk_bf16_f32 %0, %1, %2" : "=v"(r) : "v"(lo), "v"(hi)); return r; }
;     __device__ __forceinline__ void operator()(const f32x4 (&acc)[2][2][4][2], const Unit& u, int wr, int wc, int fr, int fq) const {
;     ...
;                 for (int bj = 0; bj < 2; ++bj) xv[ai][m][bj] = *(const u32x4*)(XB + (size_t)(row0 + ai * HALF + m * 16) * ldc + col0 + bj * HALF);
; #pragma unroll
;         for (int ai = 0; ai < 2; ++ai) {
; #pragma unroll
;             for (int m = 0; m < 4; ++m) { const int row = row0 + ai * HALF + m * 16;
; #pragma unroll
;                 for (int bj = 0; bj < 2; ++bj) { f32x4 v0, v1; unpack8(xv[ai][m][bj], v0, v1); v0 = v0 + acc[ai][bj][m][0]; v1 = v1 + acc[ai][bj][m][1];
;                     u32x4 w; w.x = cvt_pk_bf16(v0[0], v0[1]); w.y = cvt_pk_bf16(v0[2], v0[3]); w.z = cvt_pk_bf16(v1[0], v1[1]); w.w = cvt_pk_bf16(v1[2], v1[3]);
;                     *(u32x4*)(XB + (size_t)row * ldc + col0 + bj * HALF) = w; } }
;             asm volatile("" ::: "memory"); }
; __device__ __forceinline__ void xcd_barrier(const XcdBarrier& b) {
;     asm volatile("s_waitcnt vmcnt(0)" ::: "memory");
;     __syncthreads();
;     if (threadIdx.x == 0) {
;         unsigned* bar = b.bar;
;         __builtin_amdgcn_s_waitcnt(0);
;         unsigned nloc = b.st[0], nx = b.st[1];
;         if (nloc == 0u) { xcd_barrier_complete(bar, b.x, nloc, nx); b.st[0] = nloc; b.st[1] = nx; }
	v_cvt_pk_bf16_f32 v36, v40, v41
	v_cvt_pk_bf16_f32 v37, v42, v43
	v_lshlrev_b32_e32 v40, 16, v146
	v_cvt_pk_bf16_f32 v38, v38, v39
	v_cvt_pk_bf16_f32 v39, v44, v45
	global_store_dwordx4 v[48:49], v[36:39], off offset:256
	v_and_b32_e32 v41, 0xffff0000, v146
	v_lshlrev_b32_e32 v42, 16, v147
	v_lshlrev_b32_e32 v36, 16, v144
	v_and_b32_e32 v37, 0xffff0000, v144
	v_and_b32_e32 v43, 0xffff0000, v147
	v_pk_add_f32 v[32:33], v[32:33], v[36:37]
	v_lshlrev_b32_e32 v38, 16, v145
	v_and_b32_e32 v39, 0xffff0000, v145
	v_pk_add_f32 v[36:37], v[30:31], v[42:43]
	v_pk_add_f32 v[30:31], v[28:29], v[40:41]
	v_cvt_pk_bf16_f32 v28, v32, v33
	v_lshl_add_u64 v[32:33], s[16:17], 0, v[218:219]
	v_pk_add_f32 v[34:35], v[34:35], v[38:39]
	v_lshl_add_u64 v[32:33], v[32:33], 0, v[214:215]
	v_cvt_pk_bf16_f32 v29, v34, v35
	v_cvt_pk_bf16_f32 v30, v30, v31
	v_cvt_pk_bf16_f32 v31, v36, v37
	global_store_dwordx4 v[32:33], v[28:31], off
	v_lshlrev_b32_e32 v34, 16, v134
	v_and_b32_e32 v35, 0xffff0000, v134
	v_lshlrev_b32_e32 v28, 16, v132
	v_and_b32_e32 v29, 0xffff0000, v132
	v_lshlrev_b32_e32 v30, 16, v133
	v_and_b32_e32 v31, 0xffff0000, v133
	v_lshlrev_b32_e32 v36, 16, v135
	v_and_b32_e32 v37, 0xffff0000, v135
	v_pk_add_f32 v[26:27], v[26:27], v[30:31]
	v_pk_add_f32 v[24:25], v[24:25], v[28:29]
	v_pk_add_f32 v[28:29], v[22:23], v[36:37]
	v_pk_add_f32 v[22:23], v[20:21], v[34:35]
	v_cvt_pk_bf16_f32 v20, v24, v25
	v_cvt_pk_bf16_f32 v21, v26, v27
	v_lshlrev_b32_e32 v24, 16, v130
	v_cvt_pk_bf16_f32 v22, v22, v23
	v_cvt_pk_bf16_f32 v23, v28, v29
	global_store_dwordx4 v[32:33], v[20:23], off offset:256
	v_and_b32_e32 v25, 0xffff0000, v130
	v_lshlrev_b32_e32 v26, 16, v131
	v_lshlrev_b32_e32 v20, 16, v128
	v_and_b32_e32 v21, 0xffff0000, v128
	v_and_b32_e32 v27, 0xffff0000, v131
	v_pk_add_f32 v[16:17], v[16:17], v[20:21]
	v_lshlrev_b32_e32 v22, 16, v129
	v_and_b32_e32 v23, 0xffff0000, v129
	v_pk_add_f32 v[20:21], v[14:15], v[26:27]
	v_pk_add_f32 v[14:15], v[12:13], v[24:25]
	v_cvt_pk_bf16_f32 v12, v16, v17
	v_lshl_add_u64 v[16:17], s[16:17], 0, v[216:217]
	v_pk_add_f32 v[18:19], v[18:19], v[22:23]
	v_lshl_add_u64 v[16:17], v[16:17], 0, v[214:215]
	v_cvt_pk_bf16_f32 v13, v18, v19
	v_cvt_pk_bf16_f32 v14, v14, v15
	v_cvt_pk_bf16_f32 v15, v20, v21
	global_store_dwordx4 v[16:17], v[12:15], off
	v_lshlrev_b32_e32 v18, 16, v126
	v_and_b32_e32 v19, 0xffff0000, v126
	v_lshlrev_b32_e32 v12, 16, v124
	v_and_b32_e32 v13, 0xffff0000, v124
	v_lshlrev_b32_e32 v20, 16, v127
	v_and_b32_e32 v21, 0xffff0000, v127
	v_lshlrev_b32_e32 v14, 16, v125
	v_and_b32_e32 v15, 0xffff0000, v125
	v_pk_add_f32 v[8:9], v[8:9], v[12:13]
	v_pk_add_f32 v[12:13], v[6:7], v[20:21]
	v_pk_add_f32 v[6:7], v[4:5], v[18:19]
	v_pk_add_f32 v[10:11], v[10:11], v[14:15]
	v_cvt_pk_bf16_f32 v4, v8, v9
	s_nop 0
	v_cvt_pk_bf16_f32 v5, v10, v11
	v_cvt_pk_bf16_f32 v6, v6, v7
	v_cvt_pk_bf16_f32 v7, v12, v13
	global_store_dwordx4 v[16:17], v[4:7], off offset:256
	s_cbranch_vccnz .LBB0_1688
	s_andn2_b64 vcc, exec, s[14:15]
	s_cbranch_vccnz .LBB0_1687
	s_branch .LBB0_1687
.LBB0_1706:
	s_waitcnt vmcnt(0)
	s_and_b64 vcc, exec, s[18:19]
	s_cbranch_vccz .Lnoalign_5
	s_barrier
.Lnoalign_5:
	s_barrier
.LBB0_1707:
	v_readlane_b32 s12, v254, 0
	v_readlane_b32 s13, v254, 1
	s_getreg_b32 s14, hwreg(HW_REG_XCC_ID, 0, 4)
	s_waitcnt vmcnt(0)
	s_barrier
	s_mov_b64 s[10:11], exec
	v_readlane_b32 s16, v254, 2
	v_readlane_b32 s17, v254, 3
	s_and_b64 s[16:17], s[10:11], s[16:17]
	s_mov_b64 exec, s[16:17]
	s_cbranch_execz .LBB0_1759
	v_readlane_b32 s15, v254, 39
	s_load_dwordx2 s[12:13], s[12:13], 0x98
	s_waitcnt vmcnt(0) expcnt(0) lgkmcnt(0)
	v_mov_b32_e32 v2, s15
	ds_read_b32 v5, v2
	v_readlane_b32 s15, v254, 40
	s_and_b32 s28, s14, 15
	s_waitcnt lgkmcnt(0)
	v_cmp_ne_u32_e32 vcc, 0, v5
	v_mov_b32_e32 v2, s15
	ds_read_b32 v4, v2
	s_cbranch_vccnz .LBB0_1723
	v_readlane_b32 s14, v254, 4
	v_readlane_b32 s15, v254, 5
	s_load_dwordx2 s[18:19], s[14:15], 0x4
	s_add_u32 s14, s12, 0x4200
	s_addc_u32 s15, s13, 0
	s_add_u32 s16, s12, 0x4400
	s_addc_u32 s17, s13, 0
	v_readlane_b32 s20, v254, 54
	s_waitcnt lgkmcnt(0)
	s_mul_i32 s42, s18, s20
	s_add_u32 s18, s12, 0x4500
	s_mul_i32 s42, s42, s19
	s_addc_u32 s19, s13, 0
	s_add_u32 s20, s12, 0x4600
	s_addc_u32 s21, s13, 0
	s_add_u32 s22, s12, 0x4700
	s_addc_u32 s23, s13, 0
	s_add_u32 s24, s12, 0x4800
	s_addc_u32 s25, s13, 0
	s_add_u32 s26, s12, 0x4900
	s_addc_u32 s27, s13, 0
	s_add_u32 s36, s12, 0x4a00
	s_addc_u32 s37, s13, 0
	s_add_u32 s40, s12, 0x4b00
	s_addc_u32 s41, s13, 0
	s_add_u32 s44, s12, 0x4c00
	s_addc_u32 s45, s13, 0
	s_add_u32 s48, s12, 0x4d00
	s_addc_u32 s49, s13, 0
	s_add_u32 s50, s12, 0x4e00
	s_addc_u32 s51, s13, 0
	s_add_u32 s54, s12, 0x4f00
	s_addc_u32 s55, s13, 0
	s_add_u32 s56, s12, 0x5000
	s_addc_u32 s57, s13, 0
	s_add_u32 s52, s12, 0x5100
	s_addc_u32 s53, s13, 0
	s_add_u32 s34, s12, 0x5200
	s_addc_u32 s35, s13, 0
	s_add_u32 s58, s12, 0x5300
	s_addc_u32 s59, s13, 0
	s_mov_b32 s43, 1
	s_branch .LBB0_1711

; __device__ __forceinline__ float fast_sigmoid(float x) { return __builtin_amdgcn_rcpf(1.0f + __expf(-x)); }
; __device__ __forceinline__ float ss_rs(u64_t v) { return 1.0f / sqrtf((float)v * (1.0f / (1048576.0f * 4096.0f)) + 1e-6f); }
;     template <class ACC> __device__ __forceinline__ void operator()(const ACC (&acc)[2][2][4][2], const Unit& u, int wr, int wc, int fr, int fq) const {
;         const int row0 = u.pm * BM + wr * 64 + fr, col0 = u.pn * BM + wc * 32 + 8 * fq;
;         f32x4 db[2][2];
;         if constexpr (Q) {
; #pragma unroll
;             for (int bj = 0; bj < 2; ++bj) { db[bj][0] = *(const f32x4*)(DB + col0 + bj * HALF); db[bj][1] = *(const f32x4*)(DB + col0 + bj * HALF + 4); } }
; #pragma unroll
;         for (int ai = 0; ai < 2; ++ai)
; #pragma unroll
;           for (int mp = 0; mp < 2; ++mp) {
;             u32x4 xv[2][2], pv[2][2]; float rsv[2];
; #pragma unroll
;             for (int mm = 0; mm < 2; ++mm) { const int row = row0 + ai * HALF + (2 * mp + mm) * 16; if constexpr (Q) rsv[mm] = RA[row]; else rsv[mm] = ss_rs(SS[row]);
; #pragma unroll
;                 for (int bj = 0; bj < 2; ++bj) { xv[mm][bj] = *(const u32x4*)(XBi + (size_t)row * ldc + col0 + bj * HALF); pv[mm][bj] = *(const u32x4*)(PP + (size_t)row * ldc + col0 + bj * HALF); } }
; #pragma unroll
;             for (int mm = 0; mm < 2; ++mm) { const int m = 2 * mp + mm, row = row0 + ai * HALF + m * 16; float ss = 0.f; const float rs = rsv[mm];
; #pragma unroll
;                 for (int bj = 0; bj < 2; ++bj) { f32x4 v0, v1, p0, p1; unpack8(xv[mm][bj], v0, v1); unpack8(pv[mm][bj], p0, p1); f32x4 a0, a1;
; #pragma unroll
;                     for (int j = 0; j < 4; ++j) { if constexpr (Q) { a0[j] = (float)acc[ai][bj][m][0][j] * rs * db[bj][0][j]; a1[j] = (float)acc[ai][bj][m][1][j] * rs * db[bj][1][j]; }
;                                                   else { a0[j] = (float)acc[ai][bj][m][0][j] * rs; a1[j] = (float)acc[ai][bj][m][1][j] * rs; } }
; #pragma unroll
;                     for (int j = 0; j < 4; ++j) { v0[j] += fast_sigmoid(a0[j]) * p0[j]; v1[j] += fast_sigmoid(a1[j]) * p1[j]; }
;                     if (OUT) { float* p = OUT + (size_t)row * ldc + col0 + bj * HALF; *(f32x4*)p = v0; *(f32x4*)(p + 4) = v1; }
.Lkloop_exit_6:
.LBB0_1846:
	v_lshl_or_b32 v204, s12, 8, v218
	v_lshl_add_u32 v190, s10, 8, v216
	v_ashrrev_i32_e32 v205, 31, v204
	v_ashrrev_i32_e32 v191, 31, v190
	v_lshl_add_u64 v[32:33], v[204:205], 2, s[26:27]
	v_lshl_add_u64 v[210:211], v[190:191], 2, s[24:25]
	global_load_dwordx4 v[36:39], v[32:33], off offset:16
	global_load_dwordx4 v[40:43], v[32:33], off
	global_load_dwordx4 v[28:31], v[32:33], off offset:528
	s_nop 0
	global_load_dwordx4 v[32:35], v[32:33], off offset:512
	v_lshlrev_b64 v[140:141], 1, v[204:205]
	global_load_dword v221, v[210:211], off
	v_lshl_add_u64 v[206:207], s[18:19], 0, v[140:141]
	v_lshl_add_u64 v[208:209], s[20:21], 0, v[140:141]
	v_lshlrev_b64 v[140:141], 13, v[190:191]
	v_lshl_add_u64 v[142:143], v[206:207], 0, v[140:141]
	v_lshl_add_u64 v[140:141], v[208:209], 0, v[140:141]
	global_load_dwordx4 v[172:175], v[142:143], off
	global_load_dwordx4 v[176:179], v[140:141], off
	global_load_dwordx4 v[168:171], v[142:143], off offset:256
	global_load_dwordx4 v[164:167], v[140:141], off offset:256
	v_or_b32_e32 v212, 16, v190
	v_ashrrev_i32_e32 v213, 31, v212
	v_lshl_add_u64 v[140:141], v[212:213], 2, s[24:25]
	global_load_dword v220, v[140:141], off
	v_lshlrev_b64 v[140:141], 13, v[212:213]
	v_lshl_add_u64 v[142:143], v[206:207], 0, v[140:141]
	v_lshl_add_u64 v[140:141], v[208:209], 0, v[140:141]
	global_load_dwordx4 v[160:163], v[142:143], off
	global_load_dwordx4 v[156:159], v[140:141], off
	global_load_dwordx4 v[144:147], v[142:143], off offset:256
	s_nop 0
	global_load_dwordx4 v[140:143], v[140:141], off offset:256
	v_cvt_f32_i32_e32 v148, v148
	v_cvt_f32_i32_e32 v152, v152
	v_lshlrev_b64 v[214:215], 12, v[190:191]
	s_mov_b64 s[12:13], -1
	s_andn2_b64 vcc, exec, s[42:43]
	s_waitcnt vmcnt(0)
	v_mul_f32_e32 v148, v221, v148
	v_mul_f32_e32 v222, v36, v148
	v_cvt_f32_i32_e32 v148, v153
	v_mul_f32_e32 v152, v221, v152
	v_mul_f32_e32 v152, v40, v152
	v_mul_f32_e32 v148, v221, v148
	v_mul_f32_e32 v153, v41, v148
	v_cvt_f32_i32_e32 v148, v149
	v_mul_f32_e32 v149, 0xbfb8aa3b, v222
	v_exp_f32_e32 v149, v149
	v_mul_f32_e32 v148, v221, v148
	v_mul_f32_e32 v223, v37, v148
	v_cvt_f32_i32_e32 v148, v154
	v_add_f32_e32 v149, 1.0, v149
	v_lshlrev_b32_e32 v154, 16, v176
	v_mul_f32_e32 v148, v221, v148
	v_mul_f32_e32 v224, v42, v148
	v_cvt_f32_i32_e32 v148, v150
	v_rcp_f32_e32 v150, v149
	v_mul_f32_e32 v149, 0xbfb8aa3b, v153
	v_exp_f32_e32 v149, v149
	v_mul_f32_e32 v148, v221, v148
	v_mul_f32_e32 v225, v38, v148
	v_cvt_f32_i32_e32 v148, v155
	v_add_f32_e32 v149, 1.0, v149
	v_rcp_f32_e32 v149, v149
	v_and_b32_e32 v153, 0xffff0000, v172
	v_mul_f32_e32 v148, v221, v148
	v_mul_f32_e32 v226, v43, v148
	v_cvt_f32_i32_e32 v148, v151
	v_mul_f32_e32 v151, 0xbfb8aa3b, v223
	v_exp_f32_e32 v151, v151
	v_and_b32_e32 v155, 0xffff0000, v176
	v_mul_f32_e32 v148, v221, v148
	v_mul_f32_e32 v227, v39, v148
	v_mul_f32_e32 v148, 0xbfb8aa3b, v152
	v_exp_f32_e32 v148, v148
	v_add_f32_e32 v151, 1.0, v151
	v_rcp_f32_e32 v151, v151
	v_lshlrev_b32_e32 v152, 16, v172
	v_add_f32_e32 v148, 1.0, v148
	v_rcp_f32_e32 v148, v148
	v_lshlrev_b32_e32 v172, 16, v173
	v_and_b32_e32 v173, 0xffff0000, v173
	v_lshlrev_b32_e32 v176, 16, v177
	v_pk_fma_f32 v[148:149], v[148:149], v[154:155], v[152:153]
	v_lshlrev_b32_e32 v152, 16, v174
	v_and_b32_e32 v153, 0xffff0000, v174
	v_lshlrev_b32_e32 v154, 16, v178
	v_and_b32_e32 v155, 0xffff0000, v178
	v_pk_fma_f32 v[152:153], v[150:151], v[154:155], v[152:153]
	v_mul_f32_e32 v151, 0xbfb8aa3b, v225
	v_exp_f32_e32 v151, v151
	v_mul_f32_e32 v150, 0xbfb8aa3b, v224
	v_exp_f32_e32 v150, v150
	v_mul_f32_e32 v155, 0xbfb8aa3b, v227
	v_add_f32_e32 v151, 1.0, v151
	v_rcp_f32_e32 v154, v151
	v_mul_f32_e32 v151, 0xbfb8aa3b, v226
	v_exp_f32_e32 v151, v151
	v_exp_f32_e32 v155, v155
	v_add_f32_e32 v150, 1.0, v150
	v_rcp_f32_e32 v150, v150
	v_add_f32_e32 v151, 1.0, v151
	v_rcp_f32_e32 v151, v151
	v_add_f32_e32 v155, 1.0, v155
	v_rcp_f32_e32 v155, v155
	v_and_b32_e32 v177, 0xffff0000, v177
	v_pk_fma_f32 v[150:151], v[150:151], v[176:177], v[172:173]
	v_lshlrev_b32_e32 v172, 16, v175
	v_and_b32_e32 v173, 0xffff0000, v175
	v_lshlrev_b32_e32 v174, 16, v179
	v_and_b32_e32 v175, 0xffff0000, v179
	v_pk_fma_f32 v[154:155], v[154:155], v[174:175], v[172:173]
	v_cndmask_b32_e64 v172, 0, 1, s[42:43]
	v_cmp_ne_u32_e64 s[10:11], 1, v172
	v_lshl_add_u64 v[174:175], v[214:215], 2, s[14:15]
	s_cbranch_vccnz .LBB0_1848
	v_lshl_add_u64 v[172:173], v[204:205], 2, v[174:175]
	s_mov_b64 s[12:13], 0
	global_store_dwordx4 v[172:173], v[148:151], off
	global_store_dwordx4 v[172:173], v[152:155], off offset:16

; #define PG8_WAIT_V(n) asm volatile("s_waitcnt vmcnt(" #n ")" ::: "memory")
; #define PG8_BAR __builtin_amdgcn_s_barrier()
; template <class Epi, class Sched, bool ALIGN_EPI = false, bool SP2 = false, bool I8 = false>
; __device__ __forceinline__ void gemm_phase(PG8_LAS unsigned char* lds, const Gemm g, const Sched& S, const Epi& E) {
;     ...
;         cur = nxt; cA = nA; cB = nB; ++ui;
;         if constexpr (ALIGN_EPI) { if (wr == 1) PG8_BAR; }
;     }
;     PG8_WAIT_V(0);
;     if constexpr (!ALIGN_EPI) { if (wr == 0) PG8_BAR; }
;     PG8_BAR;
; __device__ __forceinline__ void xcd_barrier(const XcdBarrier& b) {
;     asm volatile("s_waitcnt vmcnt(0)" ::: "memory");
;     __syncthreads();
;     if (threadIdx.x == 0) {
;         unsigned* bar = b.bar;
;         __builtin_amdgcn_s_waitcnt(0);
;         unsigned nloc = b.st[0], nx = b.st[1];
;         if (nloc == 0u) { xcd_barrier_complete(bar, b.x, nloc, nx); b.st[0] = nloc; b.st[1] = nx; }
.LBB0_1942:
	s_andn2_b64 vcc, exec, s[8:9]
	s_mov_b64 s[8:9], -1
	s_cbranch_vccnz .LBB0_1835
	s_andn2_b64 vcc, exec, s[16:17]
	s_cbranch_vccnz .LBB0_1834
	s_branch .LBB0_1834
.LBB0_1945:
	s_waitcnt vmcnt(0)
	s_mov_b32 s67, 0x40000
	s_and_b64 vcc, exec, s[38:39]
	s_cbranch_vccz .Lnoalign_6
	s_barrier
.Lnoalign_6:
	s_barrier
.LBB0_1946:
	s_waitcnt lgkmcnt(0)
	v_readlane_b32 s8, v254, 0
	v_readlane_b32 s9, v254, 1
	s_getreg_b32 s10, hwreg(HW_REG_XCC_ID, 0, 4)
	s_waitcnt vmcnt(0)
	s_barrier
	s_mov_b64 s[6:7], exec
	v_readlane_b32 s12, v254, 2
	v_readlane_b32 s13, v254, 3
	s_and_b64 s[12:13], s[6:7], s[12:13]
	s_mov_b32 s58, 0x1c000
	s_mov_b32 s59, 0x54000
	s_mov_b32 s60, 0x8c000
	s_mov_b32 s61, 0xb6000
	s_mov_b32 s64, 0xc4000
	s_mov_b32 s65, 0xfc000
	s_mov_b32 s66, 0x50000
	s_mov_b64 exec, s[12:13]
	s_cbranch_execnz .LBB0_1947
	s_getpc_b64 s[98:99]
